# k-inner pairs + snake over (m,n) + alternating k direction: every MFMA transition shares the accumulator or one operand
# speedup vs baseline: 1.0159x; 1.0040x over previous
; #define PG8_STAGE(bufoff, gbase, voff) do { _Pragma("unroll") for (int _i = 0; _i < 2; ++_i) \
;         __builtin_amdgcn_global_load_lds((const unsigned*)((const char*)(gbase) + (voff)[_i]), (PG8_LAS unsigned*)(lds + (bufoff) + ldsw + _i * 8192), 16, 0, 0); } while (0)
; #define PG8_LDA(dst, b, h) do { _Pragma("unroll") for (int m = 0; m < 4; ++m) _Pragma("unroll") for (int k = 0; k < 2; ++k) dst[m][k] = *(const PG8_LAS bf16x8*)(lds + PG8_SA(b, h) + aoff + m * 2048 + k * 1024); } while (0)
; #define PG8_LDB(dst, b, h) do { _Pragma("unroll") for (int n = 0; n < 2; ++n) _Pragma("unroll") for (int k = 0; k < 2; ++k) dst[n][k] = *(const PG8_LAS bf16x8*)(lds + PG8_SB(b, h) + boff + n * 2048 + k * 1024); } while (0)
; #define PG8_MMA(ai, bj, At, Bt) do { __builtin_amdgcn_s_setprio(1); _Pragma("unroll") for (int m = 0; m < 4; ++m) _Pragma("unroll") for (int n = 0; n < 2; ++n) _Pragma("unroll") for (int k = 0; k < 2; ++k) \
;         acc[ai][bj][m][n] = __builtin_amdgcn_mfma_f32_16x16x32_bf16(Bt[n][k], At[m][k], acc[ai][bj][m][n], 0, 0, 0); __builtin_amdgcn_s_setprio(0); } while (0)
; #define PG8_WAIT_V(n) asm volatile("s_waitcnt vmcnt(" #n ")" ::: "memory")
; #define PG8_WAIT_L(n) asm volatile("s_waitcnt lgkmcnt(" #n ")" ::: "memory")
; #define PG8_BAR __builtin_amdgcn_s_barrier()
; template <class Epi, class Sched, bool ALIGN_EPI = false, bool SP2 = false>
; __device__ __forceinline__ void gemm_phase(PG8_LAS unsigned char* lds, const Gemm g, const Sched& S, const Epi& E) {
;     ...
;             const bool last = (t == nt - 2);
;             const char* a1 = cA + (size_t)(t + 1) * kstep;
;             const char* a2 = last ? nA : cA + (size_t)(t + 2) * kstep; const char* b2 = last ? nB : cB + (size_t)(t + 2) * kstep;
;             const char* a3 = a2 + kstep; const char* b3 = b2 + kstep;
;             if (last && has_next) S.a_ready(nxt);
;             if constexpr (Epi::MID) { if (t == nt / 2) E.mid(acc, cur, wr, wc, fr, fq); }
;             if constexpr (SP2) {
;             PG8_LDB(B0, 0, 0); PG8_LDB(B1, 0, 1); PG8_SCHED; PG8_LDA(At, 0, 0); PG8_STAGE(PG8_SA(1, 1), a1 + hstep, voffA);
;             PG8_WAIT_V(8); PG8_WAIT_L(0); PG8_BAR; PG8_MMA(0, 0, At, B0); PG8_MMA(0, 1, At, B1); PG8_BAR; PG8_SCHED;
;             PG8_LDA(At, 0, 1); PG8_STAGE(PG8_SB(0, 0), b2, voffB); PG8_STAGE(PG8_SB(0, 1), b2 + hstep, voffB); PG8_STAGE(PG8_SA(0, 0), a2, voffA);
.LBB0_373:
	s_add_u32 s28, s26, 0xfff80080
	s_addc_u32 s29, s27, -1
	s_add_i32 s33, 0, 0x10000
	s_cmp_eq_u32 s55, 28
	s_cselect_b32 s31, s5, s29
	s_cselect_b32 s30, s11, s28
	v_add_u32_e32 v161, s33, v155
	s_cselect_b32 s29, s19, s54
	s_cselect_b32 s28, s21, s53
	s_add_i32 s58, 0, 0x14000
	ds_read_b128 v[142:145], v161
	ds_read_b128 v[146:149], v161 offset:1024
	ds_read_b128 v[150:153], v161 offset:2048
	ds_read_b128 v[162:165], v161 offset:3072
	v_add_u32_e32 v161, s58, v155
	ds_read_b128 v[166:169], v161
	ds_read_b128 v[170:173], v161 offset:1024
	ds_read_b128 v[174:177], v161 offset:2048
	ds_read_b128 v[178:181], v161 offset:3072
	v_lshl_add_u64 v[202:203], s[26:27], 0, v[140:141]
	s_add_i32 m0, s41, 0xc000
	ds_read_b128 v[182:185], v160
	ds_read_b128 v[186:189], v160 offset:1024
	ds_read_b128 v[190:193], v160 offset:2048
	ds_read_b128 v[194:197], v160 offset:3072
	ds_read_b128 v[198:201], v160 offset:4096
	ds_read_b128 v[206:209], v160 offset:5120
	ds_read_b128 v[210:213], v160 offset:6144
	ds_read_b128 v[214:217], v160 offset:7168
	global_load_lds_dwordx4 v140, s[26:27]
	v_lshl_add_u64 v[202:203], s[26:27], 0, v[138:139]
	s_add_i32 m0, s41, 0xe000
	s_nop 0
	global_load_lds_dwordx4 v138, s[26:27]
	s_waitcnt vmcnt(8)
	s_waitcnt lgkmcnt(0)
	s_barrier
	s_setprio 1
	s_waitcnt lgkmcnt(0)
	v_mfma_f32_16x16x32_bf16 v[130:133], v[142:145], v[182:185], v[130:133]
	v_mfma_f32_16x16x32_bf16 v[130:133], v[146:149], v[186:189], v[130:133]
	v_mfma_f32_16x16x32_bf16 v[126:129], v[162:165], v[186:189], v[126:129]
	v_mfma_f32_16x16x32_bf16 v[126:129], v[150:153], v[182:185], v[126:129]
	v_mfma_f32_16x16x32_bf16 v[110:113], v[150:153], v[190:193], v[110:113]
	v_mfma_f32_16x16x32_bf16 v[110:113], v[162:165], v[194:197], v[110:113]
	v_mfma_f32_16x16x32_bf16 v[114:117], v[146:149], v[194:197], v[114:117]
	v_mfma_f32_16x16x32_bf16 v[114:117], v[142:145], v[190:193], v[114:117]
	v_mfma_f32_16x16x32_bf16 v[98:101], v[142:145], v[198:201], v[98:101]
	v_mfma_f32_16x16x32_bf16 v[98:101], v[146:149], v[206:209], v[98:101]
	v_mfma_f32_16x16x32_bf16 v[94:97], v[162:165], v[206:209], v[94:97]
	v_mfma_f32_16x16x32_bf16 v[94:97], v[150:153], v[198:201], v[94:97]
	v_mfma_f32_16x16x32_bf16 v[78:81], v[150:153], v[210:213], v[78:81]
	v_mfma_f32_16x16x32_bf16 v[78:81], v[162:165], v[214:217], v[78:81]
	v_mfma_f32_16x16x32_bf16 v[82:85], v[146:149], v[214:217], v[82:85]
	v_mfma_f32_16x16x32_bf16 v[82:85], v[142:145], v[210:213], v[82:85]
	s_setprio 0
	s_setprio 1
	v_mfma_f32_16x16x32_bf16 v[122:125], v[166:169], v[182:185], v[122:125]
	v_mfma_f32_16x16x32_bf16 v[122:125], v[170:173], v[186:189], v[122:125]
	v_mfma_f32_16x16x32_bf16 v[118:121], v[178:181], v[186:189], v[118:121]
	v_mfma_f32_16x16x32_bf16 v[118:121], v[174:177], v[182:185], v[118:121]
	v_mfma_f32_16x16x32_bf16 v[102:105], v[174:177], v[190:193], v[102:105]
	v_mfma_f32_16x16x32_bf16 v[102:105], v[178:181], v[194:197], v[102:105]
	v_mfma_f32_16x16x32_bf16 v[106:109], v[170:173], v[194:197], v[106:109]
	v_mfma_f32_16x16x32_bf16 v[106:109], v[166:169], v[190:193], v[106:109]
	v_mfma_f32_16x16x32_bf16 v[90:93], v[166:169], v[198:201], v[90:93]
	v_mfma_f32_16x16x32_bf16 v[90:93], v[170:173], v[206:209], v[90:93]
	v_mfma_f32_16x16x32_bf16 v[86:89], v[178:181], v[206:209], v[86:89]
	v_mfma_f32_16x16x32_bf16 v[86:89], v[174:177], v[198:201], v[86:89]
	v_mfma_f32_16x16x32_bf16 v[70:73], v[174:177], v[210:213], v[70:73]
	v_mfma_f32_16x16x32_bf16 v[70:73], v[178:181], v[214:217], v[70:73]
	v_mfma_f32_16x16x32_bf16 v[74:77], v[170:173], v[214:217], v[74:77]
	v_mfma_f32_16x16x32_bf16 v[74:77], v[166:169], v[210:213], v[74:77]
	s_setprio 0
	s_barrier
	s_add_i32 s33, s33, s39
	v_lshl_add_u64 v[202:203], s[28:29], 0, v[0:1]
	s_mov_b32 m0, s33
	ds_read_b128 v[182:185], v160 offset:16384
	ds_read_b128 v[186:189], v160 offset:17408
	ds_read_b128 v[190:193], v160 offset:18432
	ds_read_b128 v[194:197], v160 offset:19456
	ds_read_b128 v[198:201], v160 offset:20480
	ds_read_b128 v[206:209], v160 offset:21504
	ds_read_b128 v[210:213], v160 offset:22528
	ds_read_b128 v[214:217], v160 offset:23552
	global_load_lds_dwordx4 v0, s[28:29]
	s_add_i32 m0, s33, 0x2000
	s_add_u32 s56, s28, 0x80000
	v_lshl_add_u64 v[218:219], s[28:29], 0, v[14:15]
	s_addc_u32 s57, s29, 0
	s_add_i32 s33, s58, s39
	global_load_lds_dwordx4 v14, s[28:29]
	v_lshl_add_u64 v[220:221], s[56:57], 0, v[0:1]
	s_mov_b32 m0, s33
	v_lshl_add_u64 v[222:223], s[30:31], 0, v[134:135]
	global_load_lds_dwordx4 v0, s[56:57]
	v_lshl_add_u64 v[220:221], s[56:57], 0, v[14:15]
	s_add_i32 m0, s33, 0x2000
	s_nop 0
	global_load_lds_dwordx4 v14, s[56:57]
	v_lshl_add_u64 v[220:221], s[30:31], 0, v[136:137]
	s_mov_b32 m0, s41
	s_nop 0
	global_load_lds_dwordx4 v136, s[30:31]
	s_mov_b32 m0, s42
	s_nop 0
	global_load_lds_dwordx4 v134, s[30:31]
	s_waitcnt vmcnt(8)
	s_waitcnt lgkmcnt(0)
	s_barrier
; #define PG8_STAGE(bufoff, gbase, voff) do { _Pragma("unroll") for (int _i = 0; _i < 2; ++_i) \
;         __builtin_amdgcn_global_load_lds((const unsigned*)((const char*)(gbase) + (voff)[_i]), (PG8_LAS unsigned*)(lds + (bufoff) + ldsw + _i * 8192), 16, 0, 0); } while (0)
; #define PG8_LDA(dst, b, h) do { _Pragma("unroll") for (int m = 0; m < 4; ++m) _Pragma("unroll") for (int k = 0; k < 2; ++k) dst[m][k] = *(const PG8_LAS bf16x8*)(lds + PG8_SA(b, h) + aoff + m * 2048 + k * 1024); } while (0)
; #define PG8_LDB(dst, b, h) do { _Pragma("unroll") for (int n = 0; n < 2; ++n) _Pragma("unroll") for (int k = 0; k < 2; ++k) dst[n][k] = *(const PG8_LAS bf16x8*)(lds + PG8_SB(b, h) + boff + n * 2048 + k * 1024); } while (0)
; #define PG8_MMA(ai, bj, At, Bt) do { __builtin_amdgcn_s_setprio(1); _Pragma("unroll") for (int m = 0; m < 4; ++m) _Pragma("unroll") for (int n = 0; n < 2; ++n) _Pragma("unroll") for (int k = 0; k < 2; ++k) \
;         acc[ai][bj][m][n] = __builtin_amdgcn_mfma_f32_16x16x32_bf16(Bt[n][k], At[m][k], acc[ai][bj][m][n], 0, 0, 0); __builtin_amdgcn_s_setprio(0); } while (0)
; #define PG8_WAIT_V(n) asm volatile("s_waitcnt vmcnt(" #n ")" ::: "memory")
; #define PG8_WAIT_L(n) asm volatile("s_waitcnt lgkmcnt(" #n ")" ::: "memory")
; #define PG8_BAR __builtin_amdgcn_s_barrier()
; #define PG8_SCHED __builtin_amdgcn_sched_barrier(0)
; template <class Epi, class Sched, bool ALIGN_EPI = false, bool SP2 = false>
; __device__ __forceinline__ void gemm_phase(PG8_LAS unsigned char* lds, const Gemm g, const Sched& S, const Epi& E) {
;     ...
;             PG8_WAIT_V(8); PG8_WAIT_L(0); PG8_BAR; PG8_MMA(1, 0, At, B0); PG8_MMA(1, 1, At, B1); PG8_BAR; PG8_SCHED;
;             PG8_LDB(B0, 1, 0); PG8_LDB(B1, 1, 1); PG8_SCHED; PG8_LDA(At, 1, 0); PG8_STAGE(PG8_SA(0, 1), a2 + hstep, voffA);
;             PG8_WAIT_V(8); PG8_WAIT_L(0); PG8_BAR; PG8_MMA(0, 0, At, B0); PG8_MMA(0, 1, At, B1); PG8_BAR; PG8_SCHED;
	s_setprio 1
	s_waitcnt lgkmcnt(0)
	v_mfma_f32_16x16x32_bf16 v[66:69], v[142:145], v[182:185], v[66:69]
	v_mfma_f32_16x16x32_bf16 v[66:69], v[146:149], v[186:189], v[66:69]
	v_mfma_f32_16x16x32_bf16 v[62:65], v[162:165], v[186:189], v[62:65]
	v_mfma_f32_16x16x32_bf16 v[62:65], v[150:153], v[182:185], v[62:65]
	v_mfma_f32_16x16x32_bf16 v[46:49], v[150:153], v[190:193], v[46:49]
	v_mfma_f32_16x16x32_bf16 v[46:49], v[162:165], v[194:197], v[46:49]
	v_mfma_f32_16x16x32_bf16 v[50:53], v[146:149], v[194:197], v[50:53]
	v_mfma_f32_16x16x32_bf16 v[50:53], v[142:145], v[190:193], v[50:53]
	v_mfma_f32_16x16x32_bf16 v[34:37], v[142:145], v[198:201], v[34:37]
	v_mfma_f32_16x16x32_bf16 v[34:37], v[146:149], v[206:209], v[34:37]
	v_mfma_f32_16x16x32_bf16 v[30:33], v[162:165], v[206:209], v[30:33]
	v_mfma_f32_16x16x32_bf16 v[30:33], v[150:153], v[198:201], v[30:33]
	v_mfma_f32_16x16x32_bf16 v[10:13], v[150:153], v[210:213], v[10:13]
	v_mfma_f32_16x16x32_bf16 v[10:13], v[162:165], v[214:217], v[10:13]
	v_mfma_f32_16x16x32_bf16 v[18:21], v[146:149], v[214:217], v[18:21]
	v_mfma_f32_16x16x32_bf16 v[18:21], v[142:145], v[210:213], v[18:21]
	s_setprio 0
	s_setprio 1
	v_mfma_f32_16x16x32_bf16 v[58:61], v[166:169], v[182:185], v[58:61]
	v_mfma_f32_16x16x32_bf16 v[58:61], v[170:173], v[186:189], v[58:61]
	v_mfma_f32_16x16x32_bf16 v[54:57], v[178:181], v[186:189], v[54:57]
	v_mfma_f32_16x16x32_bf16 v[54:57], v[174:177], v[182:185], v[54:57]
	v_mfma_f32_16x16x32_bf16 v[38:41], v[174:177], v[190:193], v[38:41]
	v_mfma_f32_16x16x32_bf16 v[38:41], v[178:181], v[194:197], v[38:41]
	v_mfma_f32_16x16x32_bf16 v[42:45], v[170:173], v[194:197], v[42:45]
	v_mfma_f32_16x16x32_bf16 v[42:45], v[166:169], v[190:193], v[42:45]
	v_mfma_f32_16x16x32_bf16 v[26:29], v[166:169], v[198:201], v[26:29]
	v_mfma_f32_16x16x32_bf16 v[26:29], v[170:173], v[206:209], v[26:29]
	v_mfma_f32_16x16x32_bf16 v[22:25], v[178:181], v[206:209], v[22:25]
	v_mfma_f32_16x16x32_bf16 v[22:25], v[174:177], v[198:201], v[22:25]
	v_mfma_f32_16x16x32_bf16 v[2:5], v[174:177], v[210:213], v[2:5]
	v_mfma_f32_16x16x32_bf16 v[2:5], v[178:181], v[214:217], v[2:5]
	v_mfma_f32_16x16x32_bf16 v[6:9], v[170:173], v[214:217], v[6:9]
	v_mfma_f32_16x16x32_bf16 v[6:9], v[166:169], v[210:213], v[6:9]
	s_setprio 0
	s_barrier
	s_add_i32 s33, 0, 0x18000
	v_add_u32_e32 v161, s33, v155
	s_add_i32 s56, 0, 0x1c000
	ds_read_b128 v[142:145], v161
	ds_read_b128 v[146:149], v161 offset:1024
	ds_read_b128 v[150:153], v161 offset:2048
	ds_read_b128 v[162:165], v161 offset:3072
	v_add_u32_e32 v161, s56, v155
	ds_read_b128 v[166:169], v161
	ds_read_b128 v[170:173], v161 offset:1024
	ds_read_b128 v[174:177], v161 offset:2048
	ds_read_b128 v[178:181], v161 offset:3072
	s_add_u32 s30, s30, 0x80000
	s_addc_u32 s31, s31, 0
	s_mov_b32 m0, s43
	v_lshl_add_u64 v[224:225], s[30:31], 0, v[136:137]
	ds_read_b128 v[182:185], v160 offset:32768
	ds_read_b128 v[186:189], v160 offset:33792
	ds_read_b128 v[190:193], v160 offset:34816
	ds_read_b128 v[194:197], v160 offset:35840
	ds_read_b128 v[198:201], v160 offset:36864
	ds_read_b128 v[206:209], v160 offset:37888
	ds_read_b128 v[210:213], v160 offset:38912
	ds_read_b128 v[214:217], v160 offset:39936
	global_load_lds_dwordx4 v136, s[30:31]
	v_lshl_add_u64 v[224:225], s[30:31], 0, v[134:135]
	s_mov_b32 m0, s44
	s_nop 0
	global_load_lds_dwordx4 v134, s[30:31]
	s_waitcnt vmcnt(8)
	s_waitcnt lgkmcnt(0)
	s_barrier
	s_setprio 1
	s_waitcnt lgkmcnt(0)
	v_mfma_f32_16x16x32_bf16 v[130:133], v[142:145], v[182:185], v[130:133]
	v_mfma_f32_16x16x32_bf16 v[130:133], v[146:149], v[186:189], v[130:133]
	v_mfma_f32_16x16x32_bf16 v[126:129], v[162:165], v[186:189], v[126:129]
	v_mfma_f32_16x16x32_bf16 v[126:129], v[150:153], v[182:185], v[126:129]
	v_mfma_f32_16x16x32_bf16 v[110:113], v[150:153], v[190:193], v[110:113]
	v_mfma_f32_16x16x32_bf16 v[110:113], v[162:165], v[194:197], v[110:113]
	v_mfma_f32_16x16x32_bf16 v[114:117], v[146:149], v[194:197], v[114:117]
	v_mfma_f32_16x16x32_bf16 v[114:117], v[142:145], v[190:193], v[114:117]
	v_mfma_f32_16x16x32_bf16 v[98:101], v[142:145], v[198:201], v[98:101]
	v_mfma_f32_16x16x32_bf16 v[98:101], v[146:149], v[206:209], v[98:101]
	v_mfma_f32_16x16x32_bf16 v[94:97], v[162:165], v[206:209], v[94:97]
	v_mfma_f32_16x16x32_bf16 v[94:97], v[150:153], v[198:201], v[94:97]
	v_mfma_f32_16x16x32_bf16 v[78:81], v[150:153], v[210:213], v[78:81]
	v_mfma_f32_16x16x32_bf16 v[78:81], v[162:165], v[214:217], v[78:81]
	v_mfma_f32_16x16x32_bf16 v[82:85], v[146:149], v[214:217], v[82:85]
	v_mfma_f32_16x16x32_bf16 v[82:85], v[142:145], v[210:213], v[82:85]
	s_setprio 0
	s_setprio 1
	v_mfma_f32_16x16x32_bf16 v[122:125], v[166:169], v[182:185], v[122:125]
	v_mfma_f32_16x16x32_bf16 v[122:125], v[170:173], v[186:189], v[122:125]
	v_mfma_f32_16x16x32_bf16 v[118:121], v[178:181], v[186:189], v[118:121]
	v_mfma_f32_16x16x32_bf16 v[118:121], v[174:177], v[182:185], v[118:121]
	v_mfma_f32_16x16x32_bf16 v[102:105], v[174:177], v[190:193], v[102:105]
	v_mfma_f32_16x16x32_bf16 v[102:105], v[178:181], v[194:197], v[102:105]
	v_mfma_f32_16x16x32_bf16 v[106:109], v[170:173], v[194:197], v[106:109]
	v_mfma_f32_16x16x32_bf16 v[106:109], v[166:169], v[190:193], v[106:109]
	v_mfma_f32_16x16x32_bf16 v[90:93], v[166:169], v[198:201], v[90:93]
	v_mfma_f32_16x16x32_bf16 v[90:93], v[170:173], v[206:209], v[90:93]
	v_mfma_f32_16x16x32_bf16 v[86:89], v[178:181], v[206:209], v[86:89]
	v_mfma_f32_16x16x32_bf16 v[86:89], v[174:177], v[198:201], v[86:89]
	v_mfma_f32_16x16x32_bf16 v[70:73], v[174:177], v[210:213], v[70:73]
	v_mfma_f32_16x16x32_bf16 v[70:73], v[178:181], v[214:217], v[70:73]
	v_mfma_f32_16x16x32_bf16 v[74:77], v[170:173], v[214:217], v[74:77]
	v_mfma_f32_16x16x32_bf16 v[74:77], v[166:169], v[210:213], v[74:77]
	s_setprio 0
	s_barrier
; #define PG8_STAGE(bufoff, gbase, voff) do { _Pragma("unroll") for (int _i = 0; _i < 2; ++_i) \
;         __builtin_amdgcn_global_load_lds((const unsigned*)((const char*)(gbase) + (voff)[_i]), (PG8_LAS unsigned*)(lds + (bufoff) + ldsw + _i * 8192), 16, 0, 0); } while (0)
; #define PG8_LDA(dst, b, h) do { _Pragma("unroll") for (int m = 0; m < 4; ++m) _Pragma("unroll") for (int k = 0; k < 2; ++k) dst[m][k] = *(const PG8_LAS bf16x8*)(lds + PG8_SA(b, h) + aoff + m * 2048 + k * 1024); } while (0)
; #define PG8_MMA(ai, bj, At, Bt) do { __builtin_amdgcn_s_setprio(1); _Pragma("unroll") for (int m = 0; m < 4; ++m) _Pragma("unroll") for (int n = 0; n < 2; ++n) _Pragma("unroll") for (int k = 0; k < 2; ++k) \
;         acc[ai][bj][m][n] = __builtin_amdgcn_mfma_f32_16x16x32_bf16(Bt[n][k], At[m][k], acc[ai][bj][m][n], 0, 0, 0); __builtin_amdgcn_s_setprio(0); } while (0)
; #define PG8_WAIT_V(n) asm volatile("s_waitcnt vmcnt(" #n ")" ::: "memory")
; #define PG8_WAIT_L(n) asm volatile("s_waitcnt lgkmcnt(" #n ")" ::: "memory")
; #define PG8_BAR __builtin_amdgcn_s_barrier()
; #define PG8_SCHED __builtin_amdgcn_sched_barrier(0)
; template <class Epi, class Sched, bool ALIGN_EPI = false, bool SP2 = false>
; __device__ __forceinline__ void gemm_phase(PG8_LAS unsigned char* lds, const Gemm g, const Sched& S, const Epi& E) {
;     ...
;             PG8_LDA(At, 1, 1); PG8_STAGE(PG8_SB(1, 0), b3, voffB); PG8_STAGE(PG8_SB(1, 1), b3 + hstep, voffB); PG8_STAGE(PG8_SA(1, 0), a3, voffA);
;             PG8_WAIT_V(8); PG8_WAIT_L(0); PG8_BAR; PG8_MMA(1, 0, At, B0); PG8_MMA(1, 1, At, B1); PG8_BAR; PG8_SCHED;
	s_add_i32 s30, s33, s39
	v_lshl_add_u64 v[202:203], v[202:203], 0, s[92:93]
	s_mov_b32 m0, s30
	ds_read_b128 v[182:185], v160 offset:49152
	ds_read_b128 v[186:189], v160 offset:50176
	ds_read_b128 v[190:193], v160 offset:51200
	ds_read_b128 v[194:197], v160 offset:52224
	ds_read_b128 v[198:201], v160 offset:53248
	ds_read_b128 v[206:209], v160 offset:54272
	ds_read_b128 v[210:213], v160 offset:55296
	ds_read_b128 v[214:217], v160 offset:56320
	global_load_lds_dwordx4 v[202:203], off
	s_add_i32 m0, s30, 0x2000
	s_add_u32 s28, s28, 0x80080
	v_lshl_add_u64 v[202:203], v[218:219], 0, s[92:93]
	s_addc_u32 s29, s29, 0
	s_add_i32 s30, s56, s39
	global_load_lds_dwordx4 v[202:203], off
	v_lshl_add_u64 v[202:203], s[28:29], 0, v[0:1]
	s_mov_b32 m0, s30
	s_nop 0
	global_load_lds_dwordx4 v0, s[28:29]
	v_lshl_add_u64 v[202:203], s[28:29], 0, v[14:15]
	s_add_i32 m0, s30, 0x2000
	s_nop 0
	global_load_lds_dwordx4 v14, s[28:29]
	v_lshl_add_u64 v[202:203], v[220:221], 0, s[92:93]
	s_mov_b32 m0, s46
	s_nop 0
	global_load_lds_dwordx4 v[202:203], off
	v_lshl_add_u64 v[202:203], v[222:223], 0, s[92:93]
	s_mov_b32 m0, s47
	s_nop 0
	global_load_lds_dwordx4 v[202:203], off
	s_waitcnt vmcnt(8)
	s_waitcnt lgkmcnt(0)
	s_barrier
	s_setprio 1
	s_waitcnt lgkmcnt(0)
	v_mfma_f32_16x16x32_bf16 v[66:69], v[142:145], v[182:185], v[66:69]
	v_mfma_f32_16x16x32_bf16 v[66:69], v[146:149], v[186:189], v[66:69]
	v_mfma_f32_16x16x32_bf16 v[62:65], v[162:165], v[186:189], v[62:65]
	v_mfma_f32_16x16x32_bf16 v[62:65], v[150:153], v[182:185], v[62:65]
	v_mfma_f32_16x16x32_bf16 v[46:49], v[150:153], v[190:193], v[46:49]
	v_mfma_f32_16x16x32_bf16 v[46:49], v[162:165], v[194:197], v[46:49]
	v_mfma_f32_16x16x32_bf16 v[50:53], v[146:149], v[194:197], v[50:53]
	v_mfma_f32_16x16x32_bf16 v[50:53], v[142:145], v[190:193], v[50:53]
	v_mfma_f32_16x16x32_bf16 v[34:37], v[142:145], v[198:201], v[34:37]
	v_mfma_f32_16x16x32_bf16 v[34:37], v[146:149], v[206:209], v[34:37]
	v_mfma_f32_16x16x32_bf16 v[30:33], v[162:165], v[206:209], v[30:33]
	v_mfma_f32_16x16x32_bf16 v[30:33], v[150:153], v[198:201], v[30:33]
	v_mfma_f32_16x16x32_bf16 v[10:13], v[150:153], v[210:213], v[10:13]
	v_mfma_f32_16x16x32_bf16 v[10:13], v[162:165], v[214:217], v[10:13]
	v_mfma_f32_16x16x32_bf16 v[18:21], v[146:149], v[214:217], v[18:21]
	v_mfma_f32_16x16x32_bf16 v[18:21], v[142:145], v[210:213], v[18:21]
	s_setprio 0
	s_setprio 1
	v_mfma_f32_16x16x32_bf16 v[58:61], v[166:169], v[182:185], v[58:61]
	v_mfma_f32_16x16x32_bf16 v[58:61], v[170:173], v[186:189], v[58:61]
	v_mfma_f32_16x16x32_bf16 v[54:57], v[178:181], v[186:189], v[54:57]
	v_mfma_f32_16x16x32_bf16 v[54:57], v[174:177], v[182:185], v[54:57]
	v_mfma_f32_16x16x32_bf16 v[38:41], v[174:177], v[190:193], v[38:41]
	v_mfma_f32_16x16x32_bf16 v[38:41], v[178:181], v[194:197], v[38:41]
	v_mfma_f32_16x16x32_bf16 v[42:45], v[170:173], v[194:197], v[42:45]
	v_mfma_f32_16x16x32_bf16 v[42:45], v[166:169], v[190:193], v[42:45]
	v_mfma_f32_16x16x32_bf16 v[26:29], v[166:169], v[198:201], v[26:29]
	v_mfma_f32_16x16x32_bf16 v[26:29], v[170:173], v[206:209], v[26:29]
	v_mfma_f32_16x16x32_bf16 v[22:25], v[178:181], v[206:209], v[22:25]
	v_mfma_f32_16x16x32_bf16 v[22:25], v[174:177], v[198:201], v[22:25]
	v_mfma_f32_16x16x32_bf16 v[2:5], v[174:177], v[210:213], v[2:5]
	v_mfma_f32_16x16x32_bf16 v[2:5], v[178:181], v[214:217], v[2:5]
	v_mfma_f32_16x16x32_bf16 v[6:9], v[170:173], v[214:217], v[6:9]
	v_mfma_f32_16x16x32_bf16 v[6:9], v[166:169], v[210:213], v[6:9]
	s_setprio 0
	s_barrier
	s_add_i32 s55, s55, 2
	s_add_u32 s53, s53, 0x100
	s_addc_u32 s54, s54, 0
	s_add_u32 s26, s26, 0x100
	s_addc_u32 s27, s27, 0
	s_cmp_gt_u32 s55, 29
	s_cbranch_scc0 .LBB0_373
	s_and_b64 vcc, exec, s[14:15]
	s_cbranch_vccz .LBB0_376
	s_barrier

; #define PG8_STAGE(bufoff, gbase, voff) do { _Pragma("unroll") for (int _i = 0; _i < 2; ++_i) \
;         __builtin_amdgcn_global_load_lds((const unsigned*)((const char*)(gbase) + (voff)[_i]), (PG8_LAS unsigned*)(lds + (bufoff) + ldsw + _i * 8192), 16, 0, 0); } while (0)
; #define PG8_LDA(dst, b, h) do { _Pragma("unroll") for (int m = 0; m < 4; ++m) _Pragma("unroll") for (int k = 0; k < 2; ++k) dst[m][k] = *(const PG8_LAS bf16x8*)(lds + PG8_SA(b, h) + aoff + m * 2048 + k * 1024); } while (0)
; #define PG8_LDB(dst, b, h) do { _Pragma("unroll") for (int n = 0; n < 2; ++n) _Pragma("unroll") for (int k = 0; k < 2; ++k) dst[n][k] = *(const PG8_LAS bf16x8*)(lds + PG8_SB(b, h) + boff + n * 2048 + k * 1024); } while (0)
; #define PG8_MMA(ai, bj, At, Bt) do { __builtin_amdgcn_s_setprio(1); _Pragma("unroll") for (int m = 0; m < 4; ++m) _Pragma("unroll") for (int n = 0; n < 2; ++n) _Pragma("unroll") for (int k = 0; k < 2; ++k) \
;         acc[ai][bj][m][n] = __builtin_amdgcn_mfma_f32_16x16x32_bf16(Bt[n][k], At[m][k], acc[ai][bj][m][n], 0, 0, 0); __builtin_amdgcn_s_setprio(0); } while (0)
; #define PG8_WAIT_V(n) asm volatile("s_waitcnt vmcnt(" #n ")" ::: "memory")
; #define PG8_WAIT_L(n) asm volatile("s_waitcnt lgkmcnt(" #n ")" ::: "memory")
; #define PG8_BAR __builtin_amdgcn_s_barrier()
; template <class Epi, class Sched, bool ALIGN_EPI = false, bool SP2 = false>
; __device__ __forceinline__ void gemm_phase(PG8_LAS unsigned char* lds, const Gemm g, const Sched& S, const Epi& E) {
;     ...
;             const bool last = (t == nt - 2);
;             const char* a1 = cA + (size_t)(t + 1) * kstep;
;             const char* a2 = last ? nA : cA + (size_t)(t + 2) * kstep; const char* b2 = last ? nB : cB + (size_t)(t + 2) * kstep;
;             const char* a3 = a2 + kstep; const char* b3 = b2 + kstep;
;             if (last && has_next) S.a_ready(nxt);
;             if constexpr (Epi::MID) { if (t == nt / 2) E.mid(acc, cur, wr, wc, fr, fq); }
;             if constexpr (SP2) {
;             PG8_LDB(B0, 0, 0); PG8_LDB(B1, 0, 1); PG8_SCHED; PG8_LDA(At, 0, 0); PG8_STAGE(PG8_SA(1, 1), a1 + hstep, voffA);
;             PG8_WAIT_V(8); PG8_WAIT_L(0); PG8_BAR; PG8_MMA(0, 0, At, B0); PG8_MMA(0, 1, At, B1); PG8_BAR; PG8_SCHED;
;             PG8_LDA(At, 0, 1); PG8_STAGE(PG8_SB(0, 0), b2, voffB); PG8_STAGE(PG8_SB(0, 1), b2 + hstep, voffB); PG8_STAGE(PG8_SA(0, 0), a2, voffA);
.LBB0_482:
	s_add_u32 s22, s20, 0x100
	s_addc_u32 s23, s21, 0
	s_add_i32 s33, 0, 0x10000
	s_cmpk_eq_i32 s52, 0x54
	s_cselect_b32 s27, s5, s23
	s_cselect_b32 s26, s4, s22
	s_cselect_b32 s25, s19, s51
	s_cselect_b32 s24, s18, s50
	s_add_i32 s53, 0, 0x14000
	v_add_u32_e32 v138, s33, v199
	v_add_u32_e32 v162, s53, v199
	ds_read_b128 v[118:121], v138
	ds_read_b128 v[130:133], v138 offset:1024
	ds_read_b128 v[134:137], v138 offset:2048
	ds_read_b128 v[138:141], v138 offset:3072
	ds_read_b128 v[146:149], v162
	ds_read_b128 v[154:157], v162 offset:1024
	ds_read_b128 v[158:161], v162 offset:2048
	ds_read_b128 v[162:165], v162 offset:3072
	v_lshl_add_u64 v[202:203], s[20:21], 0, v[212:213]
	s_add_i32 m0, s37, 0xc000
	ds_read_b128 v[166:169], v201
	ds_read_b128 v[170:173], v201 offset:1024
	ds_read_b128 v[174:177], v201 offset:2048
	ds_read_b128 v[178:181], v201 offset:3072
	ds_read_b128 v[182:185], v201 offset:4096
	ds_read_b128 v[186:189], v201 offset:5120
	ds_read_b128 v[190:193], v201 offset:6144
	ds_read_b128 v[194:197], v201 offset:7168
	global_load_lds_dwordx4 v212, s[20:21]
	v_lshl_add_u64 v[202:203], s[20:21], 0, v[210:211]
	s_add_i32 m0, s37, 0xe000
	s_nop 0
	global_load_lds_dwordx4 v210, s[20:21]
	s_waitcnt vmcnt(8)
	s_waitcnt lgkmcnt(0)
	s_barrier
	s_setprio 1
	s_waitcnt lgkmcnt(0)
	v_mfma_f32_16x16x32_bf16 v[150:153], v[118:121], v[166:169], v[150:153]
	v_mfma_f32_16x16x32_bf16 v[150:153], v[130:133], v[170:173], v[150:153]
	v_mfma_f32_16x16x32_bf16 v[142:145], v[138:141], v[170:173], v[142:145]
	v_mfma_f32_16x16x32_bf16 v[142:145], v[134:137], v[166:169], v[142:145]
	v_mfma_f32_16x16x32_bf16 v[110:113], v[134:137], v[174:177], v[110:113]
	v_mfma_f32_16x16x32_bf16 v[110:113], v[138:141], v[178:181], v[110:113]
	v_mfma_f32_16x16x32_bf16 v[114:117], v[130:133], v[178:181], v[114:117]
	v_mfma_f32_16x16x32_bf16 v[114:117], v[118:121], v[174:177], v[114:117]
	v_mfma_f32_16x16x32_bf16 v[98:101], v[118:121], v[182:185], v[98:101]
	v_mfma_f32_16x16x32_bf16 v[98:101], v[130:133], v[186:189], v[98:101]
	v_mfma_f32_16x16x32_bf16 v[94:97], v[138:141], v[186:189], v[94:97]
	v_mfma_f32_16x16x32_bf16 v[94:97], v[134:137], v[182:185], v[94:97]
	v_mfma_f32_16x16x32_bf16 v[78:81], v[134:137], v[190:193], v[78:81]
	v_mfma_f32_16x16x32_bf16 v[78:81], v[138:141], v[194:197], v[78:81]
	v_mfma_f32_16x16x32_bf16 v[82:85], v[130:133], v[194:197], v[82:85]
	v_mfma_f32_16x16x32_bf16 v[82:85], v[118:121], v[190:193], v[82:85]
	s_setprio 0
	s_setprio 1
	v_mfma_f32_16x16x32_bf16 v[126:129], v[146:149], v[166:169], v[126:129]
	v_mfma_f32_16x16x32_bf16 v[126:129], v[154:157], v[170:173], v[126:129]
	v_mfma_f32_16x16x32_bf16 v[122:125], v[162:165], v[170:173], v[122:125]
	v_mfma_f32_16x16x32_bf16 v[122:125], v[158:161], v[166:169], v[122:125]
	v_mfma_f32_16x16x32_bf16 v[102:105], v[158:161], v[174:177], v[102:105]
	v_mfma_f32_16x16x32_bf16 v[102:105], v[162:165], v[178:181], v[102:105]
	v_mfma_f32_16x16x32_bf16 v[106:109], v[154:157], v[178:181], v[106:109]
	v_mfma_f32_16x16x32_bf16 v[106:109], v[146:149], v[174:177], v[106:109]
	v_mfma_f32_16x16x32_bf16 v[90:93], v[146:149], v[182:185], v[90:93]
	v_mfma_f32_16x16x32_bf16 v[90:93], v[154:157], v[186:189], v[90:93]
	v_mfma_f32_16x16x32_bf16 v[86:89], v[162:165], v[186:189], v[86:89]
	v_mfma_f32_16x16x32_bf16 v[86:89], v[158:161], v[182:185], v[86:89]
	v_mfma_f32_16x16x32_bf16 v[70:73], v[158:161], v[190:193], v[70:73]
	v_mfma_f32_16x16x32_bf16 v[70:73], v[162:165], v[194:197], v[70:73]
	v_mfma_f32_16x16x32_bf16 v[74:77], v[154:157], v[194:197], v[74:77]
	v_mfma_f32_16x16x32_bf16 v[74:77], v[146:149], v[190:193], v[74:77]
	s_setprio 0
	s_barrier
	s_add_i32 s20, s33, s36
	v_lshl_add_u64 v[202:203], s[24:25], 0, v[0:1]
	s_mov_b32 m0, s20
	ds_read_b128 v[166:169], v201 offset:16384
	ds_read_b128 v[170:173], v201 offset:17408
	ds_read_b128 v[174:177], v201 offset:18432
	ds_read_b128 v[178:181], v201 offset:19456
	ds_read_b128 v[182:185], v201 offset:20480
	ds_read_b128 v[186:189], v201 offset:21504
	ds_read_b128 v[190:193], v201 offset:22528
	ds_read_b128 v[194:197], v201 offset:23552
	global_load_lds_dwordx4 v0, s[24:25]
	s_add_i32 m0, s20, 0x2000
	s_add_u32 s20, s24, 0x160000
	v_lshl_add_u64 v[214:215], s[24:25], 0, v[208:209]
	s_addc_u32 s21, s25, 0
	s_add_i32 s33, s53, s36
	global_load_lds_dwordx4 v208, s[24:25]
	v_lshl_add_u64 v[216:217], s[20:21], 0, v[0:1]
	s_mov_b32 m0, s33
	v_lshl_add_u64 v[218:219], s[26:27], 0, v[206:207]
	global_load_lds_dwordx4 v0, s[20:21]
	v_lshl_add_u64 v[216:217], s[20:21], 0, v[208:209]
	s_add_i32 m0, s33, 0x2000
	s_nop 0
	global_load_lds_dwordx4 v208, s[20:21]
	v_lshl_add_u64 v[216:217], s[26:27], 0, v[14:15]
	s_mov_b32 m0, s37
	s_nop 0
	global_load_lds_dwordx4 v14, s[26:27]
	s_mov_b32 m0, s38
	s_nop 0
	global_load_lds_dwordx4 v206, s[26:27]
	s_waitcnt vmcnt(8)
	s_waitcnt lgkmcnt(0)
	s_barrier
; #define PG8_STAGE(bufoff, gbase, voff) do { _Pragma("unroll") for (int _i = 0; _i < 2; ++_i) \
;         __builtin_amdgcn_global_load_lds((const unsigned*)((const char*)(gbase) + (voff)[_i]), (PG8_LAS unsigned*)(lds + (bufoff) + ldsw + _i * 8192), 16, 0, 0); } while (0)
; #define PG8_LDA(dst, b, h) do { _Pragma("unroll") for (int m = 0; m < 4; ++m) _Pragma("unroll") for (int k = 0; k < 2; ++k) dst[m][k] = *(const PG8_LAS bf16x8*)(lds + PG8_SA(b, h) + aoff + m * 2048 + k * 1024); } while (0)
; #define PG8_LDB(dst, b, h) do { _Pragma("unroll") for (int n = 0; n < 2; ++n) _Pragma("unroll") for (int k = 0; k < 2; ++k) dst[n][k] = *(const PG8_LAS bf16x8*)(lds + PG8_SB(b, h) + boff + n * 2048 + k * 1024); } while (0)
; #define PG8_MMA(ai, bj, At, Bt) do { __builtin_amdgcn_s_setprio(1); _Pragma("unroll") for (int m = 0; m < 4; ++m) _Pragma("unroll") for (int n = 0; n < 2; ++n) _Pragma("unroll") for (int k = 0; k < 2; ++k) \
;         acc[ai][bj][m][n] = __builtin_amdgcn_mfma_f32_16x16x32_bf16(Bt[n][k], At[m][k], acc[ai][bj][m][n], 0, 0, 0); __builtin_amdgcn_s_setprio(0); } while (0)
; #define PG8_WAIT_V(n) asm volatile("s_waitcnt vmcnt(" #n ")" ::: "memory")
; #define PG8_WAIT_L(n) asm volatile("s_waitcnt lgkmcnt(" #n ")" ::: "memory")
; #define PG8_BAR __builtin_amdgcn_s_barrier()
; #define PG8_SCHED __builtin_amdgcn_sched_barrier(0)
; template <class Epi, class Sched, bool ALIGN_EPI = false, bool SP2 = false>
; __device__ __forceinline__ void gemm_phase(PG8_LAS unsigned char* lds, const Gemm g, const Sched& S, const Epi& E) {
;     ...
;             PG8_WAIT_V(8); PG8_WAIT_L(0); PG8_BAR; PG8_MMA(1, 0, At, B0); PG8_MMA(1, 1, At, B1); PG8_BAR; PG8_SCHED;
;             PG8_LDB(B0, 1, 0); PG8_LDB(B1, 1, 1); PG8_SCHED; PG8_LDA(At, 1, 0); PG8_STAGE(PG8_SA(0, 1), a2 + hstep, voffA);
;             PG8_WAIT_V(8); PG8_WAIT_L(0); PG8_BAR; PG8_MMA(0, 0, At, B0); PG8_MMA(0, 1, At, B1); PG8_BAR; PG8_SCHED;
	s_setprio 1
	s_waitcnt lgkmcnt(0)
	v_mfma_f32_16x16x32_bf16 v[66:69], v[118:121], v[166:169], v[66:69]
	v_mfma_f32_16x16x32_bf16 v[66:69], v[130:133], v[170:173], v[66:69]
	v_mfma_f32_16x16x32_bf16 v[62:65], v[138:141], v[170:173], v[62:65]
	v_mfma_f32_16x16x32_bf16 v[62:65], v[134:137], v[166:169], v[62:65]
	v_mfma_f32_16x16x32_bf16 v[46:49], v[134:137], v[174:177], v[46:49]
	v_mfma_f32_16x16x32_bf16 v[46:49], v[138:141], v[178:181], v[46:49]
	v_mfma_f32_16x16x32_bf16 v[50:53], v[130:133], v[178:181], v[50:53]
	v_mfma_f32_16x16x32_bf16 v[50:53], v[118:121], v[174:177], v[50:53]
	v_mfma_f32_16x16x32_bf16 v[34:37], v[118:121], v[182:185], v[34:37]
	v_mfma_f32_16x16x32_bf16 v[34:37], v[130:133], v[186:189], v[34:37]
	v_mfma_f32_16x16x32_bf16 v[30:33], v[138:141], v[186:189], v[30:33]
	v_mfma_f32_16x16x32_bf16 v[30:33], v[134:137], v[182:185], v[30:33]
	v_mfma_f32_16x16x32_bf16 v[10:13], v[134:137], v[190:193], v[10:13]
	v_mfma_f32_16x16x32_bf16 v[10:13], v[138:141], v[194:197], v[10:13]
	v_mfma_f32_16x16x32_bf16 v[18:21], v[130:133], v[194:197], v[18:21]
	v_mfma_f32_16x16x32_bf16 v[18:21], v[118:121], v[190:193], v[18:21]
	s_setprio 0
	s_setprio 1
	v_mfma_f32_16x16x32_bf16 v[58:61], v[146:149], v[166:169], v[58:61]
	v_mfma_f32_16x16x32_bf16 v[58:61], v[154:157], v[170:173], v[58:61]
	v_mfma_f32_16x16x32_bf16 v[54:57], v[162:165], v[170:173], v[54:57]
	v_mfma_f32_16x16x32_bf16 v[54:57], v[158:161], v[166:169], v[54:57]
	v_mfma_f32_16x16x32_bf16 v[38:41], v[158:161], v[174:177], v[38:41]
	v_mfma_f32_16x16x32_bf16 v[38:41], v[162:165], v[178:181], v[38:41]
	v_mfma_f32_16x16x32_bf16 v[42:45], v[154:157], v[178:181], v[42:45]
	v_mfma_f32_16x16x32_bf16 v[42:45], v[146:149], v[174:177], v[42:45]
	v_mfma_f32_16x16x32_bf16 v[26:29], v[146:149], v[182:185], v[26:29]
	v_mfma_f32_16x16x32_bf16 v[26:29], v[154:157], v[186:189], v[26:29]
	v_mfma_f32_16x16x32_bf16 v[22:25], v[162:165], v[186:189], v[22:25]
	v_mfma_f32_16x16x32_bf16 v[22:25], v[158:161], v[182:185], v[22:25]
	v_mfma_f32_16x16x32_bf16 v[2:5], v[158:161], v[190:193], v[2:5]
	v_mfma_f32_16x16x32_bf16 v[2:5], v[162:165], v[194:197], v[2:5]
	v_mfma_f32_16x16x32_bf16 v[6:9], v[154:157], v[194:197], v[6:9]
	v_mfma_f32_16x16x32_bf16 v[6:9], v[146:149], v[190:193], v[6:9]
	s_setprio 0
	s_barrier
	s_add_i32 s33, 0, 0x18000
	s_add_i32 s53, 0, 0x1c000
	v_add_u32_e32 v138, s33, v199
	v_add_u32_e32 v162, s53, v199
	ds_read_b128 v[118:121], v138
	ds_read_b128 v[130:133], v138 offset:1024
	ds_read_b128 v[134:137], v138 offset:2048
	ds_read_b128 v[138:141], v138 offset:3072
	ds_read_b128 v[146:149], v162
	ds_read_b128 v[154:157], v162 offset:1024
	ds_read_b128 v[158:161], v162 offset:2048
	ds_read_b128 v[162:165], v162 offset:3072
	s_add_u32 s20, s26, 0x160000
	s_addc_u32 s21, s27, 0
	s_mov_b32 m0, s39
	v_lshl_add_u64 v[220:221], s[20:21], 0, v[14:15]
	ds_read_b128 v[166:169], v201 offset:32768
	ds_read_b128 v[170:173], v201 offset:33792
	ds_read_b128 v[174:177], v201 offset:34816
	ds_read_b128 v[178:181], v201 offset:35840
	ds_read_b128 v[182:185], v201 offset:36864
	ds_read_b128 v[186:189], v201 offset:37888
	ds_read_b128 v[190:193], v201 offset:38912
	ds_read_b128 v[194:197], v201 offset:39936
	global_load_lds_dwordx4 v14, s[20:21]
	v_lshl_add_u64 v[220:221], s[20:21], 0, v[206:207]
	s_mov_b32 m0, s40
	s_nop 0
	global_load_lds_dwordx4 v206, s[20:21]
	s_waitcnt vmcnt(8)
	s_waitcnt lgkmcnt(0)
	s_barrier
	s_setprio 1
	s_waitcnt lgkmcnt(0)
	v_mfma_f32_16x16x32_bf16 v[150:153], v[118:121], v[166:169], v[150:153]
	v_mfma_f32_16x16x32_bf16 v[150:153], v[130:133], v[170:173], v[150:153]
	v_mfma_f32_16x16x32_bf16 v[142:145], v[138:141], v[170:173], v[142:145]
	v_mfma_f32_16x16x32_bf16 v[142:145], v[134:137], v[166:169], v[142:145]
	v_mfma_f32_16x16x32_bf16 v[110:113], v[134:137], v[174:177], v[110:113]
	v_mfma_f32_16x16x32_bf16 v[110:113], v[138:141], v[178:181], v[110:113]
	v_mfma_f32_16x16x32_bf16 v[114:117], v[130:133], v[178:181], v[114:117]
	v_mfma_f32_16x16x32_bf16 v[114:117], v[118:121], v[174:177], v[114:117]
	v_mfma_f32_16x16x32_bf16 v[98:101], v[118:121], v[182:185], v[98:101]
	v_mfma_f32_16x16x32_bf16 v[98:101], v[130:133], v[186:189], v[98:101]
	v_mfma_f32_16x16x32_bf16 v[94:97], v[138:141], v[186:189], v[94:97]
	v_mfma_f32_16x16x32_bf16 v[94:97], v[134:137], v[182:185], v[94:97]
	v_mfma_f32_16x16x32_bf16 v[78:81], v[134:137], v[190:193], v[78:81]
	v_mfma_f32_16x16x32_bf16 v[78:81], v[138:141], v[194:197], v[78:81]
	v_mfma_f32_16x16x32_bf16 v[82:85], v[130:133], v[194:197], v[82:85]
	v_mfma_f32_16x16x32_bf16 v[82:85], v[118:121], v[190:193], v[82:85]
	s_setprio 0
	s_setprio 1
	v_mfma_f32_16x16x32_bf16 v[126:129], v[146:149], v[166:169], v[126:129]
	v_mfma_f32_16x16x32_bf16 v[126:129], v[154:157], v[170:173], v[126:129]
	v_mfma_f32_16x16x32_bf16 v[122:125], v[162:165], v[170:173], v[122:125]
	v_mfma_f32_16x16x32_bf16 v[122:125], v[158:161], v[166:169], v[122:125]
	v_mfma_f32_16x16x32_bf16 v[102:105], v[158:161], v[174:177], v[102:105]
	v_mfma_f32_16x16x32_bf16 v[102:105], v[162:165], v[178:181], v[102:105]
	v_mfma_f32_16x16x32_bf16 v[106:109], v[154:157], v[178:181], v[106:109]
	v_mfma_f32_16x16x32_bf16 v[106:109], v[146:149], v[174:177], v[106:109]
	v_mfma_f32_16x16x32_bf16 v[90:93], v[146:149], v[182:185], v[90:93]
	v_mfma_f32_16x16x32_bf16 v[90:93], v[154:157], v[186:189], v[90:93]
	v_mfma_f32_16x16x32_bf16 v[86:89], v[162:165], v[186:189], v[86:89]
	v_mfma_f32_16x16x32_bf16 v[86:89], v[158:161], v[182:185], v[86:89]
	v_mfma_f32_16x16x32_bf16 v[70:73], v[158:161], v[190:193], v[70:73]
	v_mfma_f32_16x16x32_bf16 v[70:73], v[162:165], v[194:197], v[70:73]
	v_mfma_f32_16x16x32_bf16 v[74:77], v[154:157], v[194:197], v[74:77]
	v_mfma_f32_16x16x32_bf16 v[74:77], v[146:149], v[190:193], v[74:77]
	s_setprio 0
	s_barrier
; #define PG8_STAGE(bufoff, gbase, voff) do { _Pragma("unroll") for (int _i = 0; _i < 2; ++_i) \
;         __builtin_amdgcn_global_load_lds((const unsigned*)((const char*)(gbase) + (voff)[_i]), (PG8_LAS unsigned*)(lds + (bufoff) + ldsw + _i * 8192), 16, 0, 0); } while (0)
; #define PG8_LDA(dst, b, h) do { _Pragma("unroll") for (int m = 0; m < 4; ++m) _Pragma("unroll") for (int k = 0; k < 2; ++k) dst[m][k] = *(const PG8_LAS bf16x8*)(lds + PG8_SA(b, h) + aoff + m * 2048 + k * 1024); } while (0)
; #define PG8_MMA(ai, bj, At, Bt) do { __builtin_amdgcn_s_setprio(1); _Pragma("unroll") for (int m = 0; m < 4; ++m) _Pragma("unroll") for (int n = 0; n < 2; ++n) _Pragma("unroll") for (int k = 0; k < 2; ++k) \
;         acc[ai][bj][m][n] = __builtin_amdgcn_mfma_f32_16x16x32_bf16(Bt[n][k], At[m][k], acc[ai][bj][m][n], 0, 0, 0); __builtin_amdgcn_s_setprio(0); } while (0)
; #define PG8_WAIT_V(n) asm volatile("s_waitcnt vmcnt(" #n ")" ::: "memory")
; #define PG8_WAIT_L(n) asm volatile("s_waitcnt lgkmcnt(" #n ")" ::: "memory")
; #define PG8_BAR __builtin_amdgcn_s_barrier()
; #define PG8_SCHED __builtin_amdgcn_sched_barrier(0)
; template <class Epi, class Sched, bool ALIGN_EPI = false, bool SP2 = false>
; __device__ __forceinline__ void gemm_phase(PG8_LAS unsigned char* lds, const Gemm g, const Sched& S, const Epi& E) {
;     ...
;             PG8_LDA(At, 1, 1); PG8_STAGE(PG8_SB(1, 0), b3, voffB); PG8_STAGE(PG8_SB(1, 1), b3 + hstep, voffB); PG8_STAGE(PG8_SA(1, 0), a3, voffA);
;             PG8_WAIT_V(8); PG8_WAIT_L(0); PG8_BAR; PG8_MMA(1, 0, At, B0); PG8_MMA(1, 1, At, B1); PG8_BAR; PG8_SCHED;
	s_add_i32 s20, s33, s36
	v_lshl_add_u64 v[202:203], v[202:203], 0, s[92:93]
	s_mov_b32 m0, s20
	ds_read_b128 v[166:169], v201 offset:49152
	ds_read_b128 v[170:173], v201 offset:50176
	ds_read_b128 v[174:177], v201 offset:51200
	ds_read_b128 v[178:181], v201 offset:52224
	ds_read_b128 v[182:185], v201 offset:53248
	ds_read_b128 v[186:189], v201 offset:54272
	ds_read_b128 v[190:193], v201 offset:55296
	ds_read_b128 v[194:197], v201 offset:56320
	global_load_lds_dwordx4 v[202:203], off
	s_add_i32 m0, s20, 0x2000
	s_add_u32 s20, s24, 0x160080
	v_lshl_add_u64 v[202:203], v[214:215], 0, s[92:93]
	s_addc_u32 s21, s25, 0
	s_add_i32 s24, s53, s36
	global_load_lds_dwordx4 v[202:203], off
	v_lshl_add_u64 v[202:203], s[20:21], 0, v[0:1]
	s_mov_b32 m0, s24
	s_nop 0
	global_load_lds_dwordx4 v0, s[20:21]
	v_lshl_add_u64 v[202:203], s[20:21], 0, v[208:209]
	s_add_i32 m0, s24, 0x2000
	s_nop 0
	global_load_lds_dwordx4 v208, s[20:21]
	v_lshl_add_u64 v[202:203], v[216:217], 0, s[92:93]
	s_mov_b32 m0, s42
	s_nop 0
	global_load_lds_dwordx4 v[202:203], off
	v_lshl_add_u64 v[202:203], v[218:219], 0, s[92:93]
	s_mov_b32 m0, s43
	s_nop 0
	global_load_lds_dwordx4 v[202:203], off
	s_waitcnt vmcnt(8)
	s_waitcnt lgkmcnt(0)
	s_barrier
	s_setprio 1
	s_waitcnt lgkmcnt(0)
	v_mfma_f32_16x16x32_bf16 v[66:69], v[118:121], v[166:169], v[66:69]
	v_mfma_f32_16x16x32_bf16 v[66:69], v[130:133], v[170:173], v[66:69]
	v_mfma_f32_16x16x32_bf16 v[62:65], v[138:141], v[170:173], v[62:65]
	v_mfma_f32_16x16x32_bf16 v[62:65], v[134:137], v[166:169], v[62:65]
	v_mfma_f32_16x16x32_bf16 v[46:49], v[134:137], v[174:177], v[46:49]
	v_mfma_f32_16x16x32_bf16 v[46:49], v[138:141], v[178:181], v[46:49]
	v_mfma_f32_16x16x32_bf16 v[50:53], v[130:133], v[178:181], v[50:53]
	v_mfma_f32_16x16x32_bf16 v[50:53], v[118:121], v[174:177], v[50:53]
	v_mfma_f32_16x16x32_bf16 v[34:37], v[118:121], v[182:185], v[34:37]
	v_mfma_f32_16x16x32_bf16 v[34:37], v[130:133], v[186:189], v[34:37]
	v_mfma_f32_16x16x32_bf16 v[30:33], v[138:141], v[186:189], v[30:33]
	v_mfma_f32_16x16x32_bf16 v[30:33], v[134:137], v[182:185], v[30:33]
	v_mfma_f32_16x16x32_bf16 v[10:13], v[134:137], v[190:193], v[10:13]
	v_mfma_f32_16x16x32_bf16 v[10:13], v[138:141], v[194:197], v[10:13]
	v_mfma_f32_16x16x32_bf16 v[18:21], v[130:133], v[194:197], v[18:21]
	v_mfma_f32_16x16x32_bf16 v[18:21], v[118:121], v[190:193], v[18:21]
	s_setprio 0
	s_setprio 1
	v_mfma_f32_16x16x32_bf16 v[58:61], v[146:149], v[166:169], v[58:61]
	v_mfma_f32_16x16x32_bf16 v[58:61], v[154:157], v[170:173], v[58:61]
	v_mfma_f32_16x16x32_bf16 v[54:57], v[162:165], v[170:173], v[54:57]
	v_mfma_f32_16x16x32_bf16 v[54:57], v[158:161], v[166:169], v[54:57]
	v_mfma_f32_16x16x32_bf16 v[38:41], v[158:161], v[174:177], v[38:41]
	v_mfma_f32_16x16x32_bf16 v[38:41], v[162:165], v[178:181], v[38:41]
	v_mfma_f32_16x16x32_bf16 v[42:45], v[154:157], v[178:181], v[42:45]
	v_mfma_f32_16x16x32_bf16 v[42:45], v[146:149], v[174:177], v[42:45]
	v_mfma_f32_16x16x32_bf16 v[26:29], v[146:149], v[182:185], v[26:29]
	v_mfma_f32_16x16x32_bf16 v[26:29], v[154:157], v[186:189], v[26:29]
	v_mfma_f32_16x16x32_bf16 v[22:25], v[162:165], v[186:189], v[22:25]
	v_mfma_f32_16x16x32_bf16 v[22:25], v[158:161], v[182:185], v[22:25]
	v_mfma_f32_16x16x32_bf16 v[2:5], v[158:161], v[190:193], v[2:5]
	v_mfma_f32_16x16x32_bf16 v[2:5], v[162:165], v[194:197], v[2:5]
	v_mfma_f32_16x16x32_bf16 v[6:9], v[154:157], v[194:197], v[6:9]
	v_mfma_f32_16x16x32_bf16 v[6:9], v[146:149], v[190:193], v[6:9]
	s_setprio 0
	s_barrier
	s_add_i32 s52, s52, 2
	s_add_u32 s50, s50, 0x100
	s_addc_u32 s51, s51, 0
	s_cmpk_gt_u32 s52, 0x55
	s_mov_b64 s[20:21], s[22:23]
	s_cbranch_scc0 .LBB0_482
	s_and_b64 vcc, exec, s[14:15]
	s_cbranch_vccz .LBB0_485
	s_barrier

; #define PG8_STAGE(bufoff, gbase, voff) do { _Pragma("unroll") for (int _i = 0; _i < 2; ++_i) \
;         __builtin_amdgcn_global_load_lds((const unsigned*)((const char*)(gbase) + (voff)[_i]), (PG8_LAS unsigned*)(lds + (bufoff) + ldsw + _i * 8192), 16, 0, 0); } while (0)
; #define PG8_LDA(dst, b, h) do { _Pragma("unroll") for (int m = 0; m < 4; ++m) _Pragma("unroll") for (int k = 0; k < 2; ++k) dst[m][k] = *(const PG8_LAS bf16x8*)(lds + PG8_SA(b, h) + aoff + m * 2048 + k * 1024); } while (0)
; #define PG8_LDB(dst, b, h) do { _Pragma("unroll") for (int n = 0; n < 2; ++n) _Pragma("unroll") for (int k = 0; k < 2; ++k) dst[n][k] = *(const PG8_LAS bf16x8*)(lds + PG8_SB(b, h) + boff + n * 2048 + k * 1024); } while (0)
; #define PG8_MMA(ai, bj, At, Bt) do { __builtin_amdgcn_s_setprio(1); _Pragma("unroll") for (int m = 0; m < 4; ++m) _Pragma("unroll") for (int n = 0; n < 2; ++n) _Pragma("unroll") for (int k = 0; k < 2; ++k) \
;         acc[ai][bj][m][n] = __builtin_amdgcn_mfma_f32_16x16x32_bf16(Bt[n][k], At[m][k], acc[ai][bj][m][n], 0, 0, 0); __builtin_amdgcn_s_setprio(0); } while (0)
; #define PG8_WAIT_V(n) asm volatile("s_waitcnt vmcnt(" #n ")" ::: "memory")
; #define PG8_WAIT_L(n) asm volatile("s_waitcnt lgkmcnt(" #n ")" ::: "memory")
; #define PG8_BAR __builtin_amdgcn_s_barrier()
; template <class Epi, class Sched, bool ALIGN_EPI = false, bool SP2 = false>
; __device__ __forceinline__ void gemm_phase(PG8_LAS unsigned char* lds, const Gemm g, const Sched& S, const Epi& E) {
;     ...
;             const bool last = (t == nt - 2);
;             const char* a1 = cA + (size_t)(t + 1) * kstep;
;             const char* a2 = last ? nA : cA + (size_t)(t + 2) * kstep; const char* b2 = last ? nB : cB + (size_t)(t + 2) * kstep;
;             const char* a3 = a2 + kstep; const char* b3 = b2 + kstep;
;             if (last && has_next) S.a_ready(nxt);
;             if constexpr (Epi::MID) { if (t == nt / 2) E.mid(acc, cur, wr, wc, fr, fq); }
;             if constexpr (SP2) {
;             PG8_LDB(B0, 0, 0); PG8_LDB(B1, 0, 1); PG8_SCHED; PG8_LDA(At, 0, 0); PG8_STAGE(PG8_SA(1, 1), a1 + hstep, voffA);
;             PG8_WAIT_V(8); PG8_WAIT_L(0); PG8_BAR; PG8_MMA(0, 0, At, B0); PG8_MMA(0, 1, At, B1); PG8_BAR; PG8_SCHED;
;             PG8_LDA(At, 0, 1); PG8_STAGE(PG8_SB(0, 0), b2, voffB); PG8_STAGE(PG8_SB(0, 1), b2 + hstep, voffB); PG8_STAGE(PG8_SA(0, 0), a2, voffA);
.LBB0_588:
	s_add_u32 s33, s40, 0xfff80080
	s_addc_u32 s44, s41, -1
	s_add_i32 s50, 0, 0x10000
	s_cmp_eq_u32 s49, 28
	s_cselect_b32 s47, s5, s44
	s_cselect_b32 s46, s13, s33
	v_add_u32_e32 v0, s50, v153
	s_cselect_b32 s45, s31, s48
	s_cselect_b32 s44, s35, s43
	s_add_i32 s33, 0, 0x14000
	ds_read_b128 v[134:137], v0
	ds_read_b128 v[138:141], v0 offset:1024
	ds_read_b128 v[142:145], v0 offset:2048
	s_waitcnt lgkmcnt(0)
	ds_read_b128 v[168:171], v0 offset:3072
	v_add_u32_e32 v0, s33, v153
	ds_read_b128 v[172:175], v0
	ds_read_b128 v[176:179], v0 offset:1024
	ds_read_b128 v[180:183], v0 offset:2048
	ds_read_b128 v[184:187], v0 offset:3072
	v_lshl_add_u64 v[192:193], s[40:41], 0, v[166:167]
	s_add_i32 m0, s62, 0xc000
	ds_read_b128 v[188:191], v194
	ds_read_b128 v[196:199], v194 offset:1024
	ds_read_b128 v[200:203], v194 offset:2048
	ds_read_b128 v[206:209], v194 offset:3072
	ds_read_b128 v[210:213], v194 offset:4096
	ds_read_b128 v[214:217], v194 offset:5120
	ds_read_b128 v[218:221], v194 offset:6144
	ds_read_b128 v[222:225], v194 offset:7168
	global_load_lds_dwordx4 v166, s[40:41]
	v_lshl_add_u64 v[192:193], s[40:41], 0, v[164:165]
	s_add_i32 m0, s62, 0xe000
	s_nop 0
	global_load_lds_dwordx4 v164, s[40:41]
	s_waitcnt vmcnt(8)
	s_waitcnt lgkmcnt(0)
	s_barrier
	s_setprio 1
	s_waitcnt lgkmcnt(0)
	v_mfma_f32_16x16x32_bf16 v[74:77], v[134:137], v[188:191], v[74:77]
	v_mfma_f32_16x16x32_bf16 v[74:77], v[138:141], v[196:199], v[74:77]
	v_mfma_f32_16x16x32_bf16 v[62:65], v[168:171], v[196:199], v[62:65]
	v_mfma_f32_16x16x32_bf16 v[62:65], v[142:145], v[188:191], v[62:65]
	v_mfma_f32_16x16x32_bf16 v[54:57], v[142:145], v[200:203], v[54:57]
	v_mfma_f32_16x16x32_bf16 v[54:57], v[168:171], v[206:209], v[54:57]
	v_mfma_f32_16x16x32_bf16 v[58:61], v[138:141], v[206:209], v[58:61]
	v_mfma_f32_16x16x32_bf16 v[58:61], v[134:137], v[200:203], v[58:61]
	v_mfma_f32_16x16x32_bf16 v[50:53], v[134:137], v[210:213], v[50:53]
	v_mfma_f32_16x16x32_bf16 v[50:53], v[138:141], v[214:217], v[50:53]
	v_mfma_f32_16x16x32_bf16 v[46:49], v[168:171], v[214:217], v[46:49]
	v_mfma_f32_16x16x32_bf16 v[46:49], v[142:145], v[210:213], v[46:49]
	v_mfma_f32_16x16x32_bf16 v[38:41], v[142:145], v[218:221], v[38:41]
	v_mfma_f32_16x16x32_bf16 v[38:41], v[168:171], v[222:225], v[38:41]
	v_mfma_f32_16x16x32_bf16 v[42:45], v[138:141], v[222:225], v[42:45]
	v_mfma_f32_16x16x32_bf16 v[42:45], v[134:137], v[218:221], v[42:45]
	s_setprio 0
	s_setprio 1
	v_mfma_f32_16x16x32_bf16 v[130:133], v[172:175], v[188:191], v[130:133]
	v_mfma_f32_16x16x32_bf16 v[130:133], v[176:179], v[196:199], v[130:133]
	v_mfma_f32_16x16x32_bf16 v[126:129], v[184:187], v[196:199], v[126:129]
	v_mfma_f32_16x16x32_bf16 v[126:129], v[180:183], v[188:191], v[126:129]
	v_mfma_f32_16x16x32_bf16 v[118:121], v[180:183], v[200:203], v[118:121]
	v_mfma_f32_16x16x32_bf16 v[118:121], v[184:187], v[206:209], v[118:121]
	v_mfma_f32_16x16x32_bf16 v[122:125], v[176:179], v[206:209], v[122:125]
	v_mfma_f32_16x16x32_bf16 v[122:125], v[172:175], v[200:203], v[122:125]
	v_mfma_f32_16x16x32_bf16 v[114:117], v[172:175], v[210:213], v[114:117]
	v_mfma_f32_16x16x32_bf16 v[114:117], v[176:179], v[214:217], v[114:117]
	v_mfma_f32_16x16x32_bf16 v[110:113], v[184:187], v[214:217], v[110:113]
	v_mfma_f32_16x16x32_bf16 v[110:113], v[180:183], v[210:213], v[110:113]
	v_mfma_f32_16x16x32_bf16 v[102:105], v[180:183], v[218:221], v[102:105]
	v_mfma_f32_16x16x32_bf16 v[102:105], v[184:187], v[222:225], v[102:105]
	v_mfma_f32_16x16x32_bf16 v[106:109], v[176:179], v[222:225], v[106:109]
	v_mfma_f32_16x16x32_bf16 v[106:109], v[172:175], v[218:221], v[106:109]
	s_setprio 0
	s_barrier
	s_add_i32 s50, s50, s61
	v_lshl_add_u64 v[192:193], s[44:45], 0, v[146:147]
	s_mov_b32 m0, s50
	ds_read_b128 v[188:191], v194 offset:16384
	ds_read_b128 v[196:199], v194 offset:17408
	ds_read_b128 v[200:203], v194 offset:18432
	ds_read_b128 v[206:209], v194 offset:19456
	ds_read_b128 v[210:213], v194 offset:20480
	ds_read_b128 v[214:217], v194 offset:21504
	ds_read_b128 v[218:221], v194 offset:22528
	ds_read_b128 v[222:225], v194 offset:23552
	global_load_lds_dwordx4 v146, s[44:45]
	s_add_i32 m0, s50, 0x2000
	s_add_u32 s50, s44, 0x80000
	v_lshl_add_u64 v[226:227], s[44:45], 0, v[150:151]
	s_addc_u32 s51, s45, 0
	s_add_i32 s33, s33, s61
	global_load_lds_dwordx4 v150, s[44:45]
	v_lshl_add_u64 v[228:229], s[50:51], 0, v[146:147]
	s_mov_b32 m0, s33
	v_lshl_add_u64 v[230:231], s[46:47], 0, v[148:149]
	global_load_lds_dwordx4 v146, s[50:51]
	v_lshl_add_u64 v[228:229], s[50:51], 0, v[150:151]
	s_add_i32 m0, s33, 0x2000
	s_nop 0
	global_load_lds_dwordx4 v150, s[50:51]
	v_lshl_add_u64 v[228:229], s[46:47], 0, v[14:15]
	s_mov_b32 m0, s62
	s_nop 0
	global_load_lds_dwordx4 v14, s[46:47]
	s_mov_b32 m0, s63
	s_nop 0
	global_load_lds_dwordx4 v148, s[46:47]
	s_waitcnt vmcnt(8)
	s_waitcnt lgkmcnt(0)
	s_barrier
; #define PG8_STAGE(bufoff, gbase, voff) do { _Pragma("unroll") for (int _i = 0; _i < 2; ++_i) \
;         __builtin_amdgcn_global_load_lds((const unsigned*)((const char*)(gbase) + (voff)[_i]), (PG8_LAS unsigned*)(lds + (bufoff) + ldsw + _i * 8192), 16, 0, 0); } while (0)
; #define PG8_LDA(dst, b, h) do { _Pragma("unroll") for (int m = 0; m < 4; ++m) _Pragma("unroll") for (int k = 0; k < 2; ++k) dst[m][k] = *(const PG8_LAS bf16x8*)(lds + PG8_SA(b, h) + aoff + m * 2048 + k * 1024); } while (0)
; #define PG8_LDB(dst, b, h) do { _Pragma("unroll") for (int n = 0; n < 2; ++n) _Pragma("unroll") for (int k = 0; k < 2; ++k) dst[n][k] = *(const PG8_LAS bf16x8*)(lds + PG8_SB(b, h) + boff + n * 2048 + k * 1024); } while (0)
; #define PG8_MMA(ai, bj, At, Bt) do { __builtin_amdgcn_s_setprio(1); _Pragma("unroll") for (int m = 0; m < 4; ++m) _Pragma("unroll") for (int n = 0; n < 2; ++n) _Pragma("unroll") for (int k = 0; k < 2; ++k) \
;         acc[ai][bj][m][n] = __builtin_amdgcn_mfma_f32_16x16x32_bf16(Bt[n][k], At[m][k], acc[ai][bj][m][n], 0, 0, 0); __builtin_amdgcn_s_setprio(0); } while (0)
; #define PG8_WAIT_V(n) asm volatile("s_waitcnt vmcnt(" #n ")" ::: "memory")
; #define PG8_WAIT_L(n) asm volatile("s_waitcnt lgkmcnt(" #n ")" ::: "memory")
; #define PG8_BAR __builtin_amdgcn_s_barrier()
; #define PG8_SCHED __builtin_amdgcn_sched_barrier(0)
; template <class Epi, class Sched, bool ALIGN_EPI = false, bool SP2 = false>
; __device__ __forceinline__ void gemm_phase(PG8_LAS unsigned char* lds, const Gemm g, const Sched& S, const Epi& E) {
;     ...
;             PG8_WAIT_V(8); PG8_WAIT_L(0); PG8_BAR; PG8_MMA(1, 0, At, B0); PG8_MMA(1, 1, At, B1); PG8_BAR; PG8_SCHED;
;             PG8_LDB(B0, 1, 0); PG8_LDB(B1, 1, 1); PG8_SCHED; PG8_LDA(At, 1, 0); PG8_STAGE(PG8_SA(0, 1), a2 + hstep, voffA);
;             PG8_WAIT_V(8); PG8_WAIT_L(0); PG8_BAR; PG8_MMA(0, 0, At, B0); PG8_MMA(0, 1, At, B1); PG8_BAR; PG8_SCHED;
	s_setprio 1
	s_waitcnt lgkmcnt(0)
	v_mfma_f32_16x16x32_bf16 v[34:37], v[134:137], v[188:191], v[34:37]
	v_mfma_f32_16x16x32_bf16 v[34:37], v[138:141], v[196:199], v[34:37]
	v_mfma_f32_16x16x32_bf16 v[30:33], v[168:171], v[196:199], v[30:33]
	v_mfma_f32_16x16x32_bf16 v[30:33], v[142:145], v[188:191], v[30:33]
	v_mfma_f32_16x16x32_bf16 v[22:25], v[142:145], v[200:203], v[22:25]
	v_mfma_f32_16x16x32_bf16 v[22:25], v[168:171], v[206:209], v[22:25]
	v_mfma_f32_16x16x32_bf16 v[26:29], v[138:141], v[206:209], v[26:29]
	v_mfma_f32_16x16x32_bf16 v[26:29], v[134:137], v[200:203], v[26:29]
	v_mfma_f32_16x16x32_bf16 v[18:21], v[134:137], v[210:213], v[18:21]
	v_mfma_f32_16x16x32_bf16 v[18:21], v[138:141], v[214:217], v[18:21]
	v_mfma_f32_16x16x32_bf16 v[10:13], v[168:171], v[214:217], v[10:13]
	v_mfma_f32_16x16x32_bf16 v[10:13], v[142:145], v[210:213], v[10:13]
	v_mfma_f32_16x16x32_bf16 v[2:5], v[142:145], v[218:221], v[2:5]
	v_mfma_f32_16x16x32_bf16 v[2:5], v[168:171], v[222:225], v[2:5]
	v_mfma_f32_16x16x32_bf16 v[6:9], v[138:141], v[222:225], v[6:9]
	v_mfma_f32_16x16x32_bf16 v[6:9], v[134:137], v[218:221], v[6:9]
	s_setprio 0
	s_setprio 1
	v_mfma_f32_16x16x32_bf16 v[98:101], v[172:175], v[188:191], v[98:101]
	v_mfma_f32_16x16x32_bf16 v[98:101], v[176:179], v[196:199], v[98:101]
	v_mfma_f32_16x16x32_bf16 v[94:97], v[184:187], v[196:199], v[94:97]
	v_mfma_f32_16x16x32_bf16 v[94:97], v[180:183], v[188:191], v[94:97]
	v_mfma_f32_16x16x32_bf16 v[86:89], v[180:183], v[200:203], v[86:89]
	v_mfma_f32_16x16x32_bf16 v[86:89], v[184:187], v[206:209], v[86:89]
	v_mfma_f32_16x16x32_bf16 v[90:93], v[176:179], v[206:209], v[90:93]
	v_mfma_f32_16x16x32_bf16 v[90:93], v[172:175], v[200:203], v[90:93]
	v_mfma_f32_16x16x32_bf16 v[82:85], v[172:175], v[210:213], v[82:85]
	v_mfma_f32_16x16x32_bf16 v[82:85], v[176:179], v[214:217], v[82:85]
	v_mfma_f32_16x16x32_bf16 v[78:81], v[184:187], v[214:217], v[78:81]
	v_mfma_f32_16x16x32_bf16 v[78:81], v[180:183], v[210:213], v[78:81]
	v_mfma_f32_16x16x32_bf16 v[66:69], v[180:183], v[218:221], v[66:69]
	v_mfma_f32_16x16x32_bf16 v[66:69], v[184:187], v[222:225], v[66:69]
	v_mfma_f32_16x16x32_bf16 v[70:73], v[176:179], v[222:225], v[70:73]
	v_mfma_f32_16x16x32_bf16 v[70:73], v[172:175], v[218:221], v[70:73]
	s_setprio 0
	s_barrier
	s_add_i32 s33, 0, 0x18000
	v_add_u32_e32 v0, s33, v153
	s_add_i32 s50, 0, 0x1c000
	ds_read_b128 v[134:137], v0
	ds_read_b128 v[138:141], v0 offset:1024
	ds_read_b128 v[142:145], v0 offset:2048
	ds_read_b128 v[168:171], v0 offset:3072
	v_add_u32_e32 v0, s50, v153
	ds_read_b128 v[172:175], v0
	ds_read_b128 v[176:179], v0 offset:1024
	ds_read_b128 v[180:183], v0 offset:2048
	ds_read_b128 v[184:187], v0 offset:3072
	s_add_u32 s46, s46, 0x80000
	s_addc_u32 s47, s47, 0
	s_mov_b32 m0, s64
	v_lshl_add_u64 v[232:233], s[46:47], 0, v[14:15]
	ds_read_b128 v[188:191], v194 offset:32768
	ds_read_b128 v[196:199], v194 offset:33792
	ds_read_b128 v[200:203], v194 offset:34816
	ds_read_b128 v[206:209], v194 offset:35840
	ds_read_b128 v[210:213], v194 offset:36864
	ds_read_b128 v[214:217], v194 offset:37888
	ds_read_b128 v[218:221], v194 offset:38912
	ds_read_b128 v[222:225], v194 offset:39936
	global_load_lds_dwordx4 v14, s[46:47]
	v_lshl_add_u64 v[232:233], s[46:47], 0, v[148:149]
	s_mov_b32 m0, s65
	s_nop 0
	global_load_lds_dwordx4 v148, s[46:47]
	s_waitcnt vmcnt(8)
	s_waitcnt lgkmcnt(0)
	s_barrier
	s_setprio 1
	s_waitcnt lgkmcnt(0)
	v_mfma_f32_16x16x32_bf16 v[74:77], v[134:137], v[188:191], v[74:77]
	v_mfma_f32_16x16x32_bf16 v[74:77], v[138:141], v[196:199], v[74:77]
	v_mfma_f32_16x16x32_bf16 v[62:65], v[168:171], v[196:199], v[62:65]
	v_mfma_f32_16x16x32_bf16 v[62:65], v[142:145], v[188:191], v[62:65]
	v_mfma_f32_16x16x32_bf16 v[54:57], v[142:145], v[200:203], v[54:57]
	v_mfma_f32_16x16x32_bf16 v[54:57], v[168:171], v[206:209], v[54:57]
	v_mfma_f32_16x16x32_bf16 v[58:61], v[138:141], v[206:209], v[58:61]
	v_mfma_f32_16x16x32_bf16 v[58:61], v[134:137], v[200:203], v[58:61]
	v_mfma_f32_16x16x32_bf16 v[50:53], v[134:137], v[210:213], v[50:53]
	v_mfma_f32_16x16x32_bf16 v[50:53], v[138:141], v[214:217], v[50:53]
	v_mfma_f32_16x16x32_bf16 v[46:49], v[168:171], v[214:217], v[46:49]
	v_mfma_f32_16x16x32_bf16 v[46:49], v[142:145], v[210:213], v[46:49]
	v_mfma_f32_16x16x32_bf16 v[38:41], v[142:145], v[218:221], v[38:41]
	v_mfma_f32_16x16x32_bf16 v[38:41], v[168:171], v[222:225], v[38:41]
	v_mfma_f32_16x16x32_bf16 v[42:45], v[138:141], v[222:225], v[42:45]
	v_mfma_f32_16x16x32_bf16 v[42:45], v[134:137], v[218:221], v[42:45]
	s_setprio 0
	s_setprio 1
	v_mfma_f32_16x16x32_bf16 v[130:133], v[172:175], v[188:191], v[130:133]
	v_mfma_f32_16x16x32_bf16 v[130:133], v[176:179], v[196:199], v[130:133]
	v_mfma_f32_16x16x32_bf16 v[126:129], v[184:187], v[196:199], v[126:129]
	v_mfma_f32_16x16x32_bf16 v[126:129], v[180:183], v[188:191], v[126:129]
	v_mfma_f32_16x16x32_bf16 v[118:121], v[180:183], v[200:203], v[118:121]
	v_mfma_f32_16x16x32_bf16 v[118:121], v[184:187], v[206:209], v[118:121]
	v_mfma_f32_16x16x32_bf16 v[122:125], v[176:179], v[206:209], v[122:125]
	v_mfma_f32_16x16x32_bf16 v[122:125], v[172:175], v[200:203], v[122:125]
	v_mfma_f32_16x16x32_bf16 v[114:117], v[172:175], v[210:213], v[114:117]
	v_mfma_f32_16x16x32_bf16 v[114:117], v[176:179], v[214:217], v[114:117]
	v_mfma_f32_16x16x32_bf16 v[110:113], v[184:187], v[214:217], v[110:113]
	v_mfma_f32_16x16x32_bf16 v[110:113], v[180:183], v[210:213], v[110:113]
	v_mfma_f32_16x16x32_bf16 v[102:105], v[180:183], v[218:221], v[102:105]
	v_mfma_f32_16x16x32_bf16 v[102:105], v[184:187], v[222:225], v[102:105]
	v_mfma_f32_16x16x32_bf16 v[106:109], v[176:179], v[222:225], v[106:109]
	v_mfma_f32_16x16x32_bf16 v[106:109], v[172:175], v[218:221], v[106:109]
	s_setprio 0
	s_barrier
; #define PG8_STAGE(bufoff, gbase, voff) do { _Pragma("unroll") for (int _i = 0; _i < 2; ++_i) \
;         __builtin_amdgcn_global_load_lds((const unsigned*)((const char*)(gbase) + (voff)[_i]), (PG8_LAS unsigned*)(lds + (bufoff) + ldsw + _i * 8192), 16, 0, 0); } while (0)
; #define PG8_LDA(dst, b, h) do { _Pragma("unroll") for (int m = 0; m < 4; ++m) _Pragma("unroll") for (int k = 0; k < 2; ++k) dst[m][k] = *(const PG8_LAS bf16x8*)(lds + PG8_SA(b, h) + aoff + m * 2048 + k * 1024); } while (0)
; #define PG8_MMA(ai, bj, At, Bt) do { __builtin_amdgcn_s_setprio(1); _Pragma("unroll") for (int m = 0; m < 4; ++m) _Pragma("unroll") for (int n = 0; n < 2; ++n) _Pragma("unroll") for (int k = 0; k < 2; ++k) \
;         acc[ai][bj][m][n] = __builtin_amdgcn_mfma_f32_16x16x32_bf16(Bt[n][k], At[m][k], acc[ai][bj][m][n], 0, 0, 0); __builtin_amdgcn_s_setprio(0); } while (0)
; #define PG8_WAIT_V(n) asm volatile("s_waitcnt vmcnt(" #n ")" ::: "memory")
; #define PG8_WAIT_L(n) asm volatile("s_waitcnt lgkmcnt(" #n ")" ::: "memory")
; #define PG8_BAR __builtin_amdgcn_s_barrier()
; #define PG8_SCHED __builtin_amdgcn_sched_barrier(0)
; template <class Epi, class Sched, bool ALIGN_EPI = false, bool SP2 = false>
; __device__ __forceinline__ void gemm_phase(PG8_LAS unsigned char* lds, const Gemm g, const Sched& S, const Epi& E) {
;     ...
;             PG8_LDA(At, 1, 1); PG8_STAGE(PG8_SB(1, 0), b3, voffB); PG8_STAGE(PG8_SB(1, 1), b3 + hstep, voffB); PG8_STAGE(PG8_SA(1, 0), a3, voffA);
;             PG8_WAIT_V(8); PG8_WAIT_L(0); PG8_BAR; PG8_MMA(1, 0, At, B0); PG8_MMA(1, 1, At, B1); PG8_BAR; PG8_SCHED;
;     ...
;         if constexpr (ALIGN_EPI) { if (wr == 0) PG8_BAR; }
	s_add_i32 s33, s33, s61
	v_lshl_add_u64 v[192:193], v[192:193], 0, s[92:93]
	s_mov_b32 m0, s33
	ds_read_b128 v[188:191], v194 offset:49152
	ds_read_b128 v[196:199], v194 offset:50176
	ds_read_b128 v[200:203], v194 offset:51200
	ds_read_b128 v[206:209], v194 offset:52224
	ds_read_b128 v[210:213], v194 offset:53248
	ds_read_b128 v[214:217], v194 offset:54272
	ds_read_b128 v[218:221], v194 offset:55296
	ds_read_b128 v[222:225], v194 offset:56320
	global_load_lds_dwordx4 v[192:193], off
	s_add_i32 m0, s33, 0x2000
	s_add_u32 s44, s44, 0x80080
	v_lshl_add_u64 v[192:193], v[226:227], 0, s[92:93]
	s_addc_u32 s45, s45, 0
	s_add_i32 s33, s50, s61
	global_load_lds_dwordx4 v[192:193], off
	v_lshl_add_u64 v[192:193], s[44:45], 0, v[146:147]
	s_mov_b32 m0, s33
	s_nop 0
	global_load_lds_dwordx4 v146, s[44:45]
	v_lshl_add_u64 v[192:193], s[44:45], 0, v[150:151]
	s_add_i32 m0, s33, 0x2000
	s_nop 0
	global_load_lds_dwordx4 v150, s[44:45]
	v_lshl_add_u64 v[192:193], v[228:229], 0, s[92:93]
	s_mov_b32 m0, s68
	s_nop 0
	global_load_lds_dwordx4 v[192:193], off
	v_lshl_add_u64 v[192:193], v[230:231], 0, s[92:93]
	s_mov_b32 m0, s69
	s_nop 0
	global_load_lds_dwordx4 v[192:193], off
	s_waitcnt vmcnt(8)
	s_waitcnt lgkmcnt(0)
	s_barrier
	s_setprio 1
	s_waitcnt lgkmcnt(0)
	v_mfma_f32_16x16x32_bf16 v[34:37], v[134:137], v[188:191], v[34:37]
	v_mfma_f32_16x16x32_bf16 v[34:37], v[138:141], v[196:199], v[34:37]
	v_mfma_f32_16x16x32_bf16 v[30:33], v[168:171], v[196:199], v[30:33]
	v_mfma_f32_16x16x32_bf16 v[30:33], v[142:145], v[188:191], v[30:33]
	v_mfma_f32_16x16x32_bf16 v[22:25], v[142:145], v[200:203], v[22:25]
	v_mfma_f32_16x16x32_bf16 v[22:25], v[168:171], v[206:209], v[22:25]
	v_mfma_f32_16x16x32_bf16 v[26:29], v[138:141], v[206:209], v[26:29]
	v_mfma_f32_16x16x32_bf16 v[26:29], v[134:137], v[200:203], v[26:29]
	v_mfma_f32_16x16x32_bf16 v[18:21], v[134:137], v[210:213], v[18:21]
	v_mfma_f32_16x16x32_bf16 v[18:21], v[138:141], v[214:217], v[18:21]
	v_mfma_f32_16x16x32_bf16 v[10:13], v[168:171], v[214:217], v[10:13]
	v_mfma_f32_16x16x32_bf16 v[10:13], v[142:145], v[210:213], v[10:13]
	v_mfma_f32_16x16x32_bf16 v[2:5], v[142:145], v[218:221], v[2:5]
	v_mfma_f32_16x16x32_bf16 v[2:5], v[168:171], v[222:225], v[2:5]
	v_mfma_f32_16x16x32_bf16 v[6:9], v[138:141], v[222:225], v[6:9]
	v_mfma_f32_16x16x32_bf16 v[6:9], v[134:137], v[218:221], v[6:9]
	s_setprio 0
	s_setprio 1
	v_mfma_f32_16x16x32_bf16 v[98:101], v[172:175], v[188:191], v[98:101]
	v_mfma_f32_16x16x32_bf16 v[98:101], v[176:179], v[196:199], v[98:101]
	v_mfma_f32_16x16x32_bf16 v[94:97], v[184:187], v[196:199], v[94:97]
	v_mfma_f32_16x16x32_bf16 v[94:97], v[180:183], v[188:191], v[94:97]
	v_mfma_f32_16x16x32_bf16 v[86:89], v[180:183], v[200:203], v[86:89]
	v_mfma_f32_16x16x32_bf16 v[86:89], v[184:187], v[206:209], v[86:89]
	v_mfma_f32_16x16x32_bf16 v[90:93], v[176:179], v[206:209], v[90:93]
	v_mfma_f32_16x16x32_bf16 v[90:93], v[172:175], v[200:203], v[90:93]
	v_mfma_f32_16x16x32_bf16 v[82:85], v[172:175], v[210:213], v[82:85]
	v_mfma_f32_16x16x32_bf16 v[82:85], v[176:179], v[214:217], v[82:85]
	v_mfma_f32_16x16x32_bf16 v[78:81], v[184:187], v[214:217], v[78:81]
	v_mfma_f32_16x16x32_bf16 v[78:81], v[180:183], v[210:213], v[78:81]
	v_mfma_f32_16x16x32_bf16 v[66:69], v[180:183], v[218:221], v[66:69]
	v_mfma_f32_16x16x32_bf16 v[66:69], v[184:187], v[222:225], v[66:69]
	v_mfma_f32_16x16x32_bf16 v[70:73], v[176:179], v[222:225], v[70:73]
	v_mfma_f32_16x16x32_bf16 v[70:73], v[172:175], v[218:221], v[70:73]
	s_setprio 0
	s_barrier
	s_add_i32 s49, s49, 2
	s_add_u32 s43, s43, 0x100
	s_addc_u32 s48, s48, 0
	s_add_u32 s40, s40, 0x100
	s_addc_u32 s41, s41, 0
	s_cmp_gt_u32 s49, 29
	s_cbranch_scc0 .LBB0_588
	s_and_b64 vcc, exec, s[18:19]
	s_cbranch_vccz .LBB0_591
	s_barrier

; #define PG8_STAGE(bufoff, gbase, voff) do { _Pragma("unroll") for (int _i = 0; _i < 2; ++_i) \
;         __builtin_amdgcn_global_load_lds((const unsigned*)((const char*)(gbase) + (voff)[_i]), (PG8_LAS unsigned*)(lds + (bufoff) + ldsw + _i * 8192), 16, 0, 0); } while (0)
; #define PG8_LDA(dst, b, h) do { _Pragma("unroll") for (int m = 0; m < 4; ++m) _Pragma("unroll") for (int k = 0; k < 2; ++k) dst[m][k] = *(const PG8_LAS bf16x8*)(lds + PG8_SA(b, h) + aoff + m * 2048 + k * 1024); } while (0)
; #define PG8_LDB(dst, b, h) do { _Pragma("unroll") for (int n = 0; n < 2; ++n) _Pragma("unroll") for (int k = 0; k < 2; ++k) dst[n][k] = *(const PG8_LAS bf16x8*)(lds + PG8_SB(b, h) + boff + n * 2048 + k * 1024); } while (0)
; #define PG8_WAIT_V(n) asm volatile("s_waitcnt vmcnt(" #n ")" ::: "memory")
; #define PG8_WAIT_L(n) asm volatile("s_waitcnt lgkmcnt(" #n ")" ::: "memory")
; #define PG8_BAR __builtin_amdgcn_s_barrier()
; #define PG8_SCHED __builtin_amdgcn_sched_barrier(0)
; template <class Epi, class Sched, bool ALIGN_EPI = false, bool SP2 = false>
; __device__ __forceinline__ void gemm_phase(PG8_LAS unsigned char* lds, const Gemm g, const Sched& S, const Epi& E) {
;     ...
;         const bool has_next = S.next(ui + 1, nxt);
;         const char* nA = has_next ? (const char*)g.A + (size_t)nxt.pm * tstep : cA; const char* nB = has_next ? (const char*)g.Bt + (size_t)nxt.pn * tstep : cB;
;         for (int t = 0; t < nt; t += 2) {
;             const bool last = (t == nt - 2);
;             const char* a1 = cA + (size_t)(t + 1) * kstep;
;             const char* a2 = last ? nA : cA + (size_t)(t + 2) * kstep; const char* b2 = last ? nB : cB + (size_t)(t + 2) * kstep;
;             const char* a3 = a2 + kstep; const char* b3 = b2 + kstep;
;             if (last && has_next) S.a_ready(nxt);
;             if constexpr (Epi::MID) { if (t == nt / 2) E.mid(acc, cur, wr, wc, fr, fq); }
;             if constexpr (SP2) {
;             PG8_LDB(B0, 0, 0); PG8_LDB(B1, 0, 1); PG8_SCHED; PG8_LDA(At, 0, 0); PG8_STAGE(PG8_SA(1, 1), a1 + hstep, voffA);
;             PG8_WAIT_V(8); PG8_WAIT_L(0); PG8_BAR; PG8_MMA(0, 0, At, B0); PG8_MMA(0, 1, At, B1); PG8_BAR; PG8_SCHED;
;             PG8_LDA(At, 0, 1); PG8_STAGE(PG8_SB(0, 0), b2, voffB); PG8_STAGE(PG8_SB(0, 1), b2 + hstep, voffB); PG8_STAGE(PG8_SA(0, 0), a2, voffA);
.LBB0_1091:
	s_add_u32 s6, s30, s34
	s_addc_u32 s7, s31, s35
	s_add_u32 s6, s6, 0x100
	s_addc_u32 s7, s7, 0
	s_add_u32 s33, s59, s34
	s_addc_u32 s62, s60, s35
	s_cmpk_eq_i32 s34, 0xf00
	s_cselect_b32 s37, s55, s7
	s_cselect_b32 s36, s56, s6
	s_cselect_b32 s7, s57, s62
	s_cselect_b32 s6, s58, s33
	s_add_i32 s33, 0, 0x10000
	v_add_u32_e32 v0, s33, v249
	s_add_i32 s64, 0, 0x14000
	ds_read_b128 v[134:137], v0
	ds_read_b128 v[138:141], v0 offset:1024
	ds_read_b128 v[142:145], v0 offset:2048
	ds_read_b128 v[146:149], v0 offset:3072
	v_add_u32_e32 v0, s64, v249
	ds_read_b128 v[150:153], v0
	ds_read_b128 v[154:157], v0 offset:1024
	ds_read_b128 v[158:161], v0 offset:2048
	ds_read_b128 v[162:165], v0 offset:3072
	v_lshl_add_u64 v[2:3], v[172:173], 0, s[34:35]
	s_add_i32 m0, s15, 0xc000
	ds_read_b128 v[176:179], v202
	ds_read_b128 v[180:183], v202 offset:1024
	ds_read_b128 v[184:187], v202 offset:2048
	ds_read_b128 v[188:191], v202 offset:3072
	ds_read_b128 v[192:195], v202 offset:4096
	ds_read_b128 v[218:221], v202 offset:5120
	ds_read_b128 v[222:225], v202 offset:6144
	ds_read_b128 v[226:229], v202 offset:7168
	global_load_lds_dwordx4 v[2:3], off
	v_lshl_add_u64 v[2:3], v[170:171], 0, s[34:35]
	s_add_i32 m0, s15, 0xe000
	s_nop 0
	global_load_lds_dwordx4 v[2:3], off
	s_waitcnt vmcnt(8)
	s_waitcnt lgkmcnt(0)
	s_barrier
	s_setprio 1
	s_waitcnt lgkmcnt(0)
	v_mfma_f32_16x16x32_bf16 v[130:133], v[134:137], v[176:179], v[130:133]
	v_mfma_f32_16x16x32_bf16 v[130:133], v[138:141], v[180:183], v[130:133]
	v_mfma_f32_16x16x32_bf16 v[126:129], v[146:149], v[180:183], v[126:129]
	v_mfma_f32_16x16x32_bf16 v[126:129], v[142:145], v[176:179], v[126:129]
	v_mfma_f32_16x16x32_bf16 v[110:113], v[142:145], v[184:187], v[110:113]
	v_mfma_f32_16x16x32_bf16 v[110:113], v[146:149], v[188:191], v[110:113]
	v_mfma_f32_16x16x32_bf16 v[114:117], v[138:141], v[188:191], v[114:117]
	v_mfma_f32_16x16x32_bf16 v[114:117], v[134:137], v[184:187], v[114:117]
	v_mfma_f32_16x16x32_bf16 v[98:101], v[134:137], v[192:195], v[98:101]
	v_mfma_f32_16x16x32_bf16 v[98:101], v[138:141], v[218:221], v[98:101]
	v_mfma_f32_16x16x32_bf16 v[94:97], v[146:149], v[218:221], v[94:97]
	v_mfma_f32_16x16x32_bf16 v[94:97], v[142:145], v[192:195], v[94:97]
	v_mfma_f32_16x16x32_bf16 v[78:81], v[142:145], v[222:225], v[78:81]
	v_mfma_f32_16x16x32_bf16 v[78:81], v[146:149], v[226:229], v[78:81]
	v_mfma_f32_16x16x32_bf16 v[82:85], v[138:141], v[226:229], v[82:85]
	v_mfma_f32_16x16x32_bf16 v[82:85], v[134:137], v[222:225], v[82:85]
	s_setprio 0
	s_setprio 1
	v_mfma_f32_16x16x32_bf16 v[122:125], v[150:153], v[176:179], v[122:125]
	v_mfma_f32_16x16x32_bf16 v[122:125], v[154:157], v[180:183], v[122:125]
	v_mfma_f32_16x16x32_bf16 v[118:121], v[162:165], v[180:183], v[118:121]
	v_mfma_f32_16x16x32_bf16 v[118:121], v[158:161], v[176:179], v[118:121]
	v_mfma_f32_16x16x32_bf16 v[102:105], v[158:161], v[184:187], v[102:105]
	v_mfma_f32_16x16x32_bf16 v[102:105], v[162:165], v[188:191], v[102:105]
	v_mfma_f32_16x16x32_bf16 v[106:109], v[154:157], v[188:191], v[106:109]
	v_mfma_f32_16x16x32_bf16 v[106:109], v[150:153], v[184:187], v[106:109]
	v_mfma_f32_16x16x32_bf16 v[90:93], v[150:153], v[192:195], v[90:93]
	v_mfma_f32_16x16x32_bf16 v[90:93], v[154:157], v[218:221], v[90:93]
	v_mfma_f32_16x16x32_bf16 v[86:89], v[162:165], v[218:221], v[86:89]
	v_mfma_f32_16x16x32_bf16 v[86:89], v[158:161], v[192:195], v[86:89]
	v_mfma_f32_16x16x32_bf16 v[70:73], v[158:161], v[222:225], v[70:73]
	v_mfma_f32_16x16x32_bf16 v[70:73], v[162:165], v[226:229], v[70:73]
	v_mfma_f32_16x16x32_bf16 v[74:77], v[154:157], v[226:229], v[74:77]
	v_mfma_f32_16x16x32_bf16 v[74:77], v[150:153], v[222:225], v[74:77]
	s_setprio 0
	s_barrier
	s_add_i32 s33, s33, s43
	v_lshl_add_u64 v[196:197], s[6:7], 0, v[208:209]
	s_mov_b32 m0, s33
	ds_read_b128 v[176:179], v202 offset:16384
	ds_read_b128 v[180:183], v202 offset:17408
	ds_read_b128 v[184:187], v202 offset:18432
	ds_read_b128 v[188:191], v202 offset:19456
	ds_read_b128 v[192:195], v202 offset:20480
	ds_read_b128 v[218:221], v202 offset:21504
	ds_read_b128 v[222:225], v202 offset:22528
	ds_read_b128 v[226:229], v202 offset:23552
	global_load_lds_dwordx4 v208, s[6:7]
	s_add_i32 m0, s33, 0x2000
	s_add_u32 s62, s6, 0x80000
	v_lshl_add_u64 v[230:231], s[6:7], 0, v[212:213]
	s_addc_u32 s63, s7, 0
	s_add_i32 s33, s64, s43
	global_load_lds_dwordx4 v212, s[6:7]
	v_lshl_add_u64 v[2:3], s[62:63], 0, v[208:209]
	s_mov_b32 m0, s33
	v_lshl_add_u64 v[232:233], s[36:37], 0, v[206:207]
	global_load_lds_dwordx4 v208, s[62:63]
	v_lshl_add_u64 v[2:3], s[62:63], 0, v[212:213]
	s_add_i32 m0, s33, 0x2000
	v_lshl_add_u64 v[234:235], s[36:37], 0, v[210:211]
	global_load_lds_dwordx4 v212, s[62:63]
	s_mov_b32 m0, s15
	s_nop 0
	global_load_lds_dwordx4 v206, s[36:37]
	s_mov_b32 m0, s44
	s_nop 0
	global_load_lds_dwordx4 v210, s[36:37]
	s_waitcnt vmcnt(8)
	s_waitcnt lgkmcnt(0)
	s_barrier
; #define PG8_STAGE(bufoff, gbase, voff) do { _Pragma("unroll") for (int _i = 0; _i < 2; ++_i) \
;         __builtin_amdgcn_global_load_lds((const unsigned*)((const char*)(gbase) + (voff)[_i]), (PG8_LAS unsigned*)(lds + (bufoff) + ldsw + _i * 8192), 16, 0, 0); } while (0)
; #define PG8_LDA(dst, b, h) do { _Pragma("unroll") for (int m = 0; m < 4; ++m) _Pragma("unroll") for (int k = 0; k < 2; ++k) dst[m][k] = *(const PG8_LAS bf16x8*)(lds + PG8_SA(b, h) + aoff + m * 2048 + k * 1024); } while (0)
; #define PG8_LDB(dst, b, h) do { _Pragma("unroll") for (int n = 0; n < 2; ++n) _Pragma("unroll") for (int k = 0; k < 2; ++k) dst[n][k] = *(const PG8_LAS bf16x8*)(lds + PG8_SB(b, h) + boff + n * 2048 + k * 1024); } while (0)
; #define PG8_MMA(ai, bj, At, Bt) do { __builtin_amdgcn_s_setprio(1); _Pragma("unroll") for (int m = 0; m < 4; ++m) _Pragma("unroll") for (int n = 0; n < 2; ++n) _Pragma("unroll") for (int k = 0; k < 2; ++k) \
;         acc[ai][bj][m][n] = __builtin_amdgcn_mfma_f32_16x16x32_bf16(Bt[n][k], At[m][k], acc[ai][bj][m][n], 0, 0, 0); __builtin_amdgcn_s_setprio(0); } while (0)
; #define PG8_WAIT_V(n) asm volatile("s_waitcnt vmcnt(" #n ")" ::: "memory")
; #define PG8_WAIT_L(n) asm volatile("s_waitcnt lgkmcnt(" #n ")" ::: "memory")
; #define PG8_BAR __builtin_amdgcn_s_barrier()
; #define PG8_SCHED __builtin_amdgcn_sched_barrier(0)
; template <class Epi, class Sched, bool ALIGN_EPI = false, bool SP2 = false>
; __device__ __forceinline__ void gemm_phase(PG8_LAS unsigned char* lds, const Gemm g, const Sched& S, const Epi& E) {
;     ...
;             PG8_WAIT_V(8); PG8_WAIT_L(0); PG8_BAR; PG8_MMA(1, 0, At, B0); PG8_MMA(1, 1, At, B1); PG8_BAR; PG8_SCHED;
;             PG8_LDB(B0, 1, 0); PG8_LDB(B1, 1, 1); PG8_SCHED; PG8_LDA(At, 1, 0); PG8_STAGE(PG8_SA(0, 1), a2 + hstep, voffA);
;             PG8_WAIT_V(8); PG8_WAIT_L(0); PG8_BAR; PG8_MMA(0, 0, At, B0); PG8_MMA(0, 1, At, B1); PG8_BAR; PG8_SCHED;
	s_setprio 1
	s_waitcnt lgkmcnt(0)
	v_mfma_f32_16x16x32_bf16 v[66:69], v[134:137], v[176:179], v[66:69]
	v_mfma_f32_16x16x32_bf16 v[66:69], v[138:141], v[180:183], v[66:69]
	v_mfma_f32_16x16x32_bf16 v[62:65], v[146:149], v[180:183], v[62:65]
	v_mfma_f32_16x16x32_bf16 v[62:65], v[142:145], v[176:179], v[62:65]
	v_mfma_f32_16x16x32_bf16 v[46:49], v[142:145], v[184:187], v[46:49]
	v_mfma_f32_16x16x32_bf16 v[46:49], v[146:149], v[188:191], v[46:49]
	v_mfma_f32_16x16x32_bf16 v[50:53], v[138:141], v[188:191], v[50:53]
	v_mfma_f32_16x16x32_bf16 v[50:53], v[134:137], v[184:187], v[50:53]
	v_mfma_f32_16x16x32_bf16 v[34:37], v[134:137], v[192:195], v[34:37]
	v_mfma_f32_16x16x32_bf16 v[34:37], v[138:141], v[218:221], v[34:37]
	v_mfma_f32_16x16x32_bf16 v[30:33], v[146:149], v[218:221], v[30:33]
	v_mfma_f32_16x16x32_bf16 v[30:33], v[142:145], v[192:195], v[30:33]
	v_mfma_f32_16x16x32_bf16 v[12:15], v[142:145], v[222:225], v[12:15]
	v_mfma_f32_16x16x32_bf16 v[12:15], v[146:149], v[226:229], v[12:15]
	v_mfma_f32_16x16x32_bf16 v[18:21], v[138:141], v[226:229], v[18:21]
	v_mfma_f32_16x16x32_bf16 v[18:21], v[134:137], v[222:225], v[18:21]
	s_setprio 0
	s_setprio 1
	v_mfma_f32_16x16x32_bf16 v[58:61], v[150:153], v[176:179], v[58:61]
	v_mfma_f32_16x16x32_bf16 v[54:57], v[158:161], v[176:179], v[54:57]
	v_mfma_f32_16x16x32_bf16 v[42:45], v[150:153], v[184:187], v[42:45]
	v_mfma_f32_16x16x32_bf16 v[38:41], v[158:161], v[184:187], v[38:41]
	v_mfma_f32_16x16x32_bf16 v[26:29], v[150:153], v[192:195], v[26:29]
	v_mfma_f32_16x16x32_bf16 v[22:25], v[158:161], v[192:195], v[22:25]
	v_mfma_f32_16x16x32_bf16 v[8:11], v[150:153], v[222:225], v[8:11]
	v_mfma_f32_16x16x32_bf16 v[2:5], v[158:161], v[222:225], v[4:7]
	v_mfma_f32_16x16x32_bf16 v[58:61], v[154:157], v[180:183], v[58:61]
	v_mfma_f32_16x16x32_bf16 v[54:57], v[162:165], v[180:183], v[54:57]
	v_mfma_f32_16x16x32_bf16 v[42:45], v[154:157], v[188:191], v[42:45]
	v_mfma_f32_16x16x32_bf16 v[38:41], v[162:165], v[188:191], v[38:41]
	v_mfma_f32_16x16x32_bf16 v[26:29], v[154:157], v[218:221], v[26:29]
	v_mfma_f32_16x16x32_bf16 v[22:25], v[162:165], v[218:221], v[22:25]
	v_mfma_f32_16x16x32_bf16 v[8:11], v[154:157], v[226:229], v[8:11]
	v_mfma_f32_16x16x32_bf16 v[2:5], v[162:165], v[226:229], v[2:5]
	s_setprio 0
	s_barrier
	s_add_i32 s33, 0, 0x18000
	v_add_u32_e32 v0, s33, v249
	s_add_i32 s62, 0, 0x1c000
	ds_read_b128 v[134:137], v0
	ds_read_b128 v[138:141], v0 offset:1024
	ds_read_b128 v[142:145], v0 offset:2048
	ds_read_b128 v[146:149], v0 offset:3072
	v_add_u32_e32 v0, s62, v249
	ds_read_b128 v[150:153], v0
	ds_read_b128 v[154:157], v0 offset:1024
	ds_read_b128 v[158:161], v0 offset:2048
	ds_read_b128 v[162:165], v0 offset:3072
	s_add_u32 s36, s36, 0x80000
	s_addc_u32 s37, s37, 0
	s_mov_b32 m0, s45
	v_lshl_add_u64 v[6:7], s[36:37], 0, v[206:207]
	ds_read_b128 v[176:179], v202 offset:32768
	ds_read_b128 v[180:183], v202 offset:33792
	ds_read_b128 v[184:187], v202 offset:34816
	ds_read_b128 v[188:191], v202 offset:35840
	ds_read_b128 v[192:195], v202 offset:36864
	ds_read_b128 v[218:221], v202 offset:37888
	ds_read_b128 v[222:225], v202 offset:38912
	ds_read_b128 v[226:229], v202 offset:39936
	global_load_lds_dwordx4 v206, s[36:37]
	v_lshl_add_u64 v[6:7], s[36:37], 0, v[210:211]
	s_mov_b32 m0, s46
	s_nop 0
	global_load_lds_dwordx4 v210, s[36:37]
	s_waitcnt vmcnt(8)
	s_waitcnt lgkmcnt(0)
	s_barrier
	s_setprio 1
	s_waitcnt lgkmcnt(0)
	v_mfma_f32_16x16x32_bf16 v[130:133], v[134:137], v[176:179], v[130:133]
	v_mfma_f32_16x16x32_bf16 v[130:133], v[138:141], v[180:183], v[130:133]
	v_mfma_f32_16x16x32_bf16 v[126:129], v[146:149], v[180:183], v[126:129]
	v_mfma_f32_16x16x32_bf16 v[126:129], v[142:145], v[176:179], v[126:129]
	v_mfma_f32_16x16x32_bf16 v[110:113], v[142:145], v[184:187], v[110:113]
	v_mfma_f32_16x16x32_bf16 v[110:113], v[146:149], v[188:191], v[110:113]
	v_mfma_f32_16x16x32_bf16 v[114:117], v[138:141], v[188:191], v[114:117]
	v_mfma_f32_16x16x32_bf16 v[114:117], v[134:137], v[184:187], v[114:117]
	v_mfma_f32_16x16x32_bf16 v[98:101], v[134:137], v[192:195], v[98:101]
	v_mfma_f32_16x16x32_bf16 v[98:101], v[138:141], v[218:221], v[98:101]
	v_mfma_f32_16x16x32_bf16 v[94:97], v[146:149], v[218:221], v[94:97]
	v_mfma_f32_16x16x32_bf16 v[94:97], v[142:145], v[192:195], v[94:97]
	v_mfma_f32_16x16x32_bf16 v[78:81], v[142:145], v[222:225], v[78:81]
	v_mfma_f32_16x16x32_bf16 v[78:81], v[146:149], v[226:229], v[78:81]
	v_mfma_f32_16x16x32_bf16 v[82:85], v[138:141], v[226:229], v[82:85]
	v_mfma_f32_16x16x32_bf16 v[82:85], v[134:137], v[222:225], v[82:85]
	s_setprio 0
	s_setprio 1
	v_mfma_f32_16x16x32_bf16 v[122:125], v[150:153], v[176:179], v[122:125]
	v_mfma_f32_16x16x32_bf16 v[122:125], v[154:157], v[180:183], v[122:125]
	v_mfma_f32_16x16x32_bf16 v[118:121], v[162:165], v[180:183], v[118:121]
	v_mfma_f32_16x16x32_bf16 v[118:121], v[158:161], v[176:179], v[118:121]
	v_mfma_f32_16x16x32_bf16 v[102:105], v[158:161], v[184:187], v[102:105]
	v_mfma_f32_16x16x32_bf16 v[102:105], v[162:165], v[188:191], v[102:105]
	v_mfma_f32_16x16x32_bf16 v[106:109], v[154:157], v[188:191], v[106:109]
	v_mfma_f32_16x16x32_bf16 v[106:109], v[150:153], v[184:187], v[106:109]
	v_mfma_f32_16x16x32_bf16 v[90:93], v[150:153], v[192:195], v[90:93]
	v_mfma_f32_16x16x32_bf16 v[90:93], v[154:157], v[218:221], v[90:93]
	v_mfma_f32_16x16x32_bf16 v[86:89], v[162:165], v[218:221], v[86:89]
	v_mfma_f32_16x16x32_bf16 v[86:89], v[158:161], v[192:195], v[86:89]
	v_mfma_f32_16x16x32_bf16 v[70:73], v[158:161], v[222:225], v[70:73]
	v_mfma_f32_16x16x32_bf16 v[70:73], v[162:165], v[226:229], v[70:73]
	v_mfma_f32_16x16x32_bf16 v[74:77], v[154:157], v[226:229], v[74:77]
	v_mfma_f32_16x16x32_bf16 v[74:77], v[150:153], v[222:225], v[74:77]
	s_setprio 0
	s_barrier
; #define PG8_STAGE(bufoff, gbase, voff) do { _Pragma("unroll") for (int _i = 0; _i < 2; ++_i) \
;         __builtin_amdgcn_global_load_lds((const unsigned*)((const char*)(gbase) + (voff)[_i]), (PG8_LAS unsigned*)(lds + (bufoff) + ldsw + _i * 8192), 16, 0, 0); } while (0)
; #define PG8_LDA(dst, b, h) do { _Pragma("unroll") for (int m = 0; m < 4; ++m) _Pragma("unroll") for (int k = 0; k < 2; ++k) dst[m][k] = *(const PG8_LAS bf16x8*)(lds + PG8_SA(b, h) + aoff + m * 2048 + k * 1024); } while (0)
; #define PG8_MMA(ai, bj, At, Bt) do { __builtin_amdgcn_s_setprio(1); _Pragma("unroll") for (int m = 0; m < 4; ++m) _Pragma("unroll") for (int n = 0; n < 2; ++n) _Pragma("unroll") for (int k = 0; k < 2; ++k) \
;         acc[ai][bj][m][n] = __builtin_amdgcn_mfma_f32_16x16x32_bf16(Bt[n][k], At[m][k], acc[ai][bj][m][n], 0, 0, 0); __builtin_amdgcn_s_setprio(0); } while (0)
; #define PG8_WAIT_V(n) asm volatile("s_waitcnt vmcnt(" #n ")" ::: "memory")
; #define PG8_WAIT_L(n) asm volatile("s_waitcnt lgkmcnt(" #n ")" ::: "memory")
; #define PG8_BAR __builtin_amdgcn_s_barrier()
; #define PG8_SCHED __builtin_amdgcn_sched_barrier(0)
; template <class Epi, class Sched, bool ALIGN_EPI = false, bool SP2 = false>
; __device__ __forceinline__ void gemm_phase(PG8_LAS unsigned char* lds, const Gemm g, const Sched& S, const Epi& E) {
;     ...
;             PG8_LDA(At, 1, 1); PG8_STAGE(PG8_SB(1, 0), b3, voffB); PG8_STAGE(PG8_SB(1, 1), b3 + hstep, voffB); PG8_STAGE(PG8_SA(1, 0), a3, voffA);
;             PG8_WAIT_V(8); PG8_WAIT_L(0); PG8_BAR; PG8_MMA(1, 0, At, B0); PG8_MMA(1, 1, At, B1); PG8_BAR; PG8_SCHED;
	s_add_i32 s33, s33, s43
	v_lshl_add_u64 v[6:7], v[196:197], 0, s[92:93]
	s_mov_b32 m0, s33
	ds_read_b128 v[176:179], v202 offset:49152
	ds_read_b128 v[180:183], v202 offset:50176
	ds_read_b128 v[184:187], v202 offset:51200
	ds_read_b128 v[188:191], v202 offset:52224
	ds_read_b128 v[192:195], v202 offset:53248
	ds_read_b128 v[218:221], v202 offset:54272
	ds_read_b128 v[222:225], v202 offset:55296
	ds_read_b128 v[226:229], v202 offset:56320
	global_load_lds_dwordx4 v[6:7], off
	s_add_i32 m0, s33, 0x2000
	s_add_u32 s6, s6, 0x80080
	v_lshl_add_u64 v[6:7], v[230:231], 0, s[92:93]
	s_addc_u32 s7, s7, 0
	s_add_i32 s33, s62, s43
	global_load_lds_dwordx4 v[6:7], off
	v_lshl_add_u64 v[6:7], s[6:7], 0, v[208:209]
	s_mov_b32 m0, s33
	s_nop 0
	global_load_lds_dwordx4 v208, s[6:7]
	v_lshl_add_u64 v[6:7], s[6:7], 0, v[212:213]
	s_add_i32 m0, s33, 0x2000
	s_nop 0
	global_load_lds_dwordx4 v212, s[6:7]
	v_lshl_add_u64 v[6:7], v[232:233], 0, s[92:93]
	s_mov_b32 m0, s48
	s_nop 0
	global_load_lds_dwordx4 v[6:7], off
	v_lshl_add_u64 v[6:7], v[234:235], 0, s[92:93]
	s_mov_b32 m0, s49
	s_nop 0
	global_load_lds_dwordx4 v[6:7], off
	s_waitcnt vmcnt(8)
	s_waitcnt lgkmcnt(0)
	s_barrier
	s_setprio 1
	s_waitcnt lgkmcnt(0)
	v_mfma_f32_16x16x32_bf16 v[66:69], v[134:137], v[176:179], v[66:69]
	v_mfma_f32_16x16x32_bf16 v[66:69], v[138:141], v[180:183], v[66:69]
	v_mfma_f32_16x16x32_bf16 v[62:65], v[146:149], v[180:183], v[62:65]
	v_mfma_f32_16x16x32_bf16 v[62:65], v[142:145], v[176:179], v[62:65]
	v_mfma_f32_16x16x32_bf16 v[46:49], v[142:145], v[184:187], v[46:49]
	v_mfma_f32_16x16x32_bf16 v[46:49], v[146:149], v[188:191], v[46:49]
	v_mfma_f32_16x16x32_bf16 v[50:53], v[138:141], v[188:191], v[50:53]
	v_mfma_f32_16x16x32_bf16 v[50:53], v[134:137], v[184:187], v[50:53]
	v_mfma_f32_16x16x32_bf16 v[34:37], v[134:137], v[192:195], v[34:37]
	v_mfma_f32_16x16x32_bf16 v[34:37], v[138:141], v[218:221], v[34:37]
	v_mfma_f32_16x16x32_bf16 v[30:33], v[146:149], v[218:221], v[30:33]
	v_mfma_f32_16x16x32_bf16 v[30:33], v[142:145], v[192:195], v[30:33]
	v_mfma_f32_16x16x32_bf16 v[12:15], v[142:145], v[222:225], v[12:15]
	v_mfma_f32_16x16x32_bf16 v[12:15], v[146:149], v[226:229], v[12:15]
	v_mfma_f32_16x16x32_bf16 v[18:21], v[138:141], v[226:229], v[18:21]
	v_mfma_f32_16x16x32_bf16 v[18:21], v[134:137], v[222:225], v[18:21]
	s_setprio 0
	s_setprio 1
	v_mfma_f32_16x16x32_bf16 v[58:61], v[150:153], v[176:179], v[58:61]
	v_mfma_f32_16x16x32_bf16 v[54:57], v[158:161], v[176:179], v[54:57]
	v_mfma_f32_16x16x32_bf16 v[42:45], v[150:153], v[184:187], v[42:45]
	v_mfma_f32_16x16x32_bf16 v[38:41], v[158:161], v[184:187], v[38:41]
	v_mfma_f32_16x16x32_bf16 v[26:29], v[150:153], v[192:195], v[26:29]
	v_mfma_f32_16x16x32_bf16 v[22:25], v[158:161], v[192:195], v[22:25]
	v_mfma_f32_16x16x32_bf16 v[6:9], v[150:153], v[222:225], v[8:11]
	v_mfma_f32_16x16x32_bf16 v[2:5], v[158:161], v[222:225], v[2:5]
	v_mfma_f32_16x16x32_bf16 v[58:61], v[154:157], v[180:183], v[58:61]
	v_mfma_f32_16x16x32_bf16 v[54:57], v[162:165], v[180:183], v[54:57]
	v_mfma_f32_16x16x32_bf16 v[42:45], v[154:157], v[188:191], v[42:45]
	v_mfma_f32_16x16x32_bf16 v[38:41], v[162:165], v[188:191], v[38:41]
	v_mfma_f32_16x16x32_bf16 v[26:29], v[154:157], v[218:221], v[26:29]
	v_mfma_f32_16x16x32_bf16 v[22:25], v[162:165], v[218:221], v[22:25]
	v_mfma_f32_16x16x32_bf16 v[8:11], v[154:157], v[226:229], v[6:9]
	v_mfma_f32_16x16x32_bf16 v[4:7], v[162:165], v[226:229], v[2:5]
	s_setprio 0
	s_barrier
	s_add_i32 s61, s61, 2
	s_add_u32 s34, s34, 0x100
	s_addc_u32 s35, s35, 0
	s_cmp_gt_u32 s61, 29
	s_cbranch_scc1 .LBB0_1096

; #define PG8_STAGE(bufoff, gbase, voff) do { _Pragma("unroll") for (int _i = 0; _i < 2; ++_i) \
;         __builtin_amdgcn_global_load_lds((const unsigned*)((const char*)(gbase) + (voff)[_i]), (PG8_LAS unsigned*)(lds + (bufoff) + ldsw + _i * 8192), 16, 0, 0); } while (0)
; #define PG8_LDA(dst, b, h) do { _Pragma("unroll") for (int m = 0; m < 4; ++m) _Pragma("unroll") for (int k = 0; k < 2; ++k) dst[m][k] = *(const PG8_LAS bf16x8*)(lds + PG8_SA(b, h) + aoff + m * 2048 + k * 1024); } while (0)
; #define PG8_LDB(dst, b, h) do { _Pragma("unroll") for (int n = 0; n < 2; ++n) _Pragma("unroll") for (int k = 0; k < 2; ++k) dst[n][k] = *(const PG8_LAS bf16x8*)(lds + PG8_SB(b, h) + boff + n * 2048 + k * 1024); } while (0)
; #define PG8_WAIT_V(n) asm volatile("s_waitcnt vmcnt(" #n ")" ::: "memory")
; #define PG8_WAIT_L(n) asm volatile("s_waitcnt lgkmcnt(" #n ")" ::: "memory")
; #define PG8_BAR __builtin_amdgcn_s_barrier()
; #define PG8_SCHED __builtin_amdgcn_sched_barrier(0)
; template <class Epi, class Sched, bool ALIGN_EPI = false, bool SP2 = false>
; __device__ __forceinline__ void gemm_phase(PG8_LAS unsigned char* lds, const Gemm g, const Sched& S, const Epi& E) {
;     ...
;         const bool has_next = S.next(ui + 1, nxt);
;         const char* nA = has_next ? (const char*)g.A + (size_t)nxt.pm * tstep : cA; const char* nB = has_next ? (const char*)g.Bt + (size_t)nxt.pn * tstep : cB;
;         for (int t = 0; t < nt; t += 2) {
;             const bool last = (t == nt - 2);
;             const char* a1 = cA + (size_t)(t + 1) * kstep;
;             const char* a2 = last ? nA : cA + (size_t)(t + 2) * kstep; const char* b2 = last ? nB : cB + (size_t)(t + 2) * kstep;
;             const char* a3 = a2 + kstep; const char* b3 = b2 + kstep;
;             if (last && has_next) S.a_ready(nxt);
;             if constexpr (Epi::MID) { if (t == nt / 2) E.mid(acc, cur, wr, wc, fr, fq); }
;             if constexpr (SP2) {
;             PG8_LDB(B0, 0, 0); PG8_LDB(B1, 0, 1); PG8_SCHED; PG8_LDA(At, 0, 0); PG8_STAGE(PG8_SA(1, 1), a1 + hstep, voffA);
;             PG8_WAIT_V(8); PG8_WAIT_L(0); PG8_BAR; PG8_MMA(0, 0, At, B0); PG8_MMA(0, 1, At, B1); PG8_BAR; PG8_SCHED;
;             PG8_LDA(At, 0, 1); PG8_STAGE(PG8_SB(0, 0), b2, voffB); PG8_STAGE(PG8_SB(0, 1), b2 + hstep, voffB); PG8_STAGE(PG8_SA(0, 0), a2, voffA);
.LBB0_1223:
	s_add_u32 s28, s26, 0xfff80080
	s_addc_u32 s29, s27, -1
	s_add_i32 s33, 0, 0x10000
	s_cmp_eq_u32 s56, 28
	s_cselect_b32 s31, s5, s29
	s_cselect_b32 s30, s11, s28
	v_add_u32_e32 v161, s33, v155
	s_cselect_b32 s29, s19, s55
	s_cselect_b32 s28, s21, s54
	s_add_i32 s57, 0, 0x14000
	ds_read_b128 v[142:145], v161
	ds_read_b128 v[146:149], v161 offset:1024
	ds_read_b128 v[150:153], v161 offset:2048
	ds_read_b128 v[162:165], v161 offset:3072
	v_add_u32_e32 v161, s57, v155
	ds_read_b128 v[166:169], v161
	ds_read_b128 v[170:173], v161 offset:1024
	ds_read_b128 v[174:177], v161 offset:2048
	ds_read_b128 v[178:181], v161 offset:3072
	v_lshl_add_u64 v[202:203], s[26:27], 0, v[140:141]
	s_add_i32 m0, s42, 0xc000
	ds_read_b128 v[182:185], v160
	ds_read_b128 v[186:189], v160 offset:1024
	ds_read_b128 v[190:193], v160 offset:2048
	ds_read_b128 v[194:197], v160 offset:3072
	ds_read_b128 v[198:201], v160 offset:4096
	ds_read_b128 v[206:209], v160 offset:5120
	ds_read_b128 v[210:213], v160 offset:6144
	ds_read_b128 v[214:217], v160 offset:7168
	global_load_lds_dwordx4 v140, s[26:27]
	v_lshl_add_u64 v[202:203], s[26:27], 0, v[138:139]
	s_add_i32 m0, s42, 0xe000
	s_nop 0
	global_load_lds_dwordx4 v138, s[26:27]
	s_waitcnt vmcnt(8)
	s_waitcnt lgkmcnt(0)
	s_barrier
	s_setprio 1
	s_waitcnt lgkmcnt(0)
	v_mfma_f32_16x16x32_bf16 v[130:133], v[142:145], v[182:185], v[130:133]
	v_mfma_f32_16x16x32_bf16 v[130:133], v[146:149], v[186:189], v[130:133]
	v_mfma_f32_16x16x32_bf16 v[126:129], v[162:165], v[186:189], v[126:129]
	v_mfma_f32_16x16x32_bf16 v[126:129], v[150:153], v[182:185], v[126:129]
	v_mfma_f32_16x16x32_bf16 v[110:113], v[150:153], v[190:193], v[110:113]
	v_mfma_f32_16x16x32_bf16 v[110:113], v[162:165], v[194:197], v[110:113]
	v_mfma_f32_16x16x32_bf16 v[114:117], v[146:149], v[194:197], v[114:117]
	v_mfma_f32_16x16x32_bf16 v[114:117], v[142:145], v[190:193], v[114:117]
	v_mfma_f32_16x16x32_bf16 v[98:101], v[142:145], v[198:201], v[98:101]
	v_mfma_f32_16x16x32_bf16 v[98:101], v[146:149], v[206:209], v[98:101]
	v_mfma_f32_16x16x32_bf16 v[94:97], v[162:165], v[206:209], v[94:97]
	v_mfma_f32_16x16x32_bf16 v[94:97], v[150:153], v[198:201], v[94:97]
	v_mfma_f32_16x16x32_bf16 v[78:81], v[150:153], v[210:213], v[78:81]
	v_mfma_f32_16x16x32_bf16 v[78:81], v[162:165], v[214:217], v[78:81]
	v_mfma_f32_16x16x32_bf16 v[82:85], v[146:149], v[214:217], v[82:85]
	v_mfma_f32_16x16x32_bf16 v[82:85], v[142:145], v[210:213], v[82:85]
	s_setprio 0
	s_setprio 1
	v_mfma_f32_16x16x32_bf16 v[122:125], v[166:169], v[182:185], v[122:125]
	v_mfma_f32_16x16x32_bf16 v[122:125], v[170:173], v[186:189], v[122:125]
	v_mfma_f32_16x16x32_bf16 v[118:121], v[178:181], v[186:189], v[118:121]
	v_mfma_f32_16x16x32_bf16 v[118:121], v[174:177], v[182:185], v[118:121]
	v_mfma_f32_16x16x32_bf16 v[102:105], v[174:177], v[190:193], v[102:105]
	v_mfma_f32_16x16x32_bf16 v[102:105], v[178:181], v[194:197], v[102:105]
	v_mfma_f32_16x16x32_bf16 v[106:109], v[170:173], v[194:197], v[106:109]
	v_mfma_f32_16x16x32_bf16 v[106:109], v[166:169], v[190:193], v[106:109]
	v_mfma_f32_16x16x32_bf16 v[90:93], v[166:169], v[198:201], v[90:93]
	v_mfma_f32_16x16x32_bf16 v[90:93], v[170:173], v[206:209], v[90:93]
	v_mfma_f32_16x16x32_bf16 v[86:89], v[178:181], v[206:209], v[86:89]
	v_mfma_f32_16x16x32_bf16 v[86:89], v[174:177], v[198:201], v[86:89]
	v_mfma_f32_16x16x32_bf16 v[70:73], v[174:177], v[210:213], v[70:73]
	v_mfma_f32_16x16x32_bf16 v[70:73], v[178:181], v[214:217], v[70:73]
	v_mfma_f32_16x16x32_bf16 v[74:77], v[170:173], v[214:217], v[74:77]
	v_mfma_f32_16x16x32_bf16 v[74:77], v[166:169], v[210:213], v[74:77]
	s_setprio 0
	s_barrier
	s_add_i32 s33, s33, s40
	v_lshl_add_u64 v[202:203], s[28:29], 0, v[0:1]
	s_mov_b32 m0, s33
	ds_read_b128 v[182:185], v160 offset:16384
	ds_read_b128 v[186:189], v160 offset:17408
	ds_read_b128 v[190:193], v160 offset:18432
	ds_read_b128 v[194:197], v160 offset:19456
	ds_read_b128 v[198:201], v160 offset:20480
	ds_read_b128 v[206:209], v160 offset:21504
	ds_read_b128 v[210:213], v160 offset:22528
	ds_read_b128 v[214:217], v160 offset:23552
	global_load_lds_dwordx4 v0, s[28:29]
	s_add_i32 m0, s33, 0x2000
	s_add_u32 s58, s28, 0x80000
	v_lshl_add_u64 v[218:219], s[28:29], 0, v[14:15]
	s_addc_u32 s59, s29, 0
	s_add_i32 s33, s57, s40
	global_load_lds_dwordx4 v14, s[28:29]
	v_lshl_add_u64 v[220:221], s[58:59], 0, v[0:1]
	s_mov_b32 m0, s33
	v_lshl_add_u64 v[222:223], s[30:31], 0, v[134:135]
	global_load_lds_dwordx4 v0, s[58:59]
	v_lshl_add_u64 v[220:221], s[58:59], 0, v[14:15]
	s_add_i32 m0, s33, 0x2000
	s_nop 0
	global_load_lds_dwordx4 v14, s[58:59]
	v_lshl_add_u64 v[220:221], s[30:31], 0, v[136:137]
	s_mov_b32 m0, s42
	s_nop 0
	global_load_lds_dwordx4 v136, s[30:31]
	s_mov_b32 m0, s43
	s_nop 0
	global_load_lds_dwordx4 v134, s[30:31]
	s_waitcnt vmcnt(8)
	s_waitcnt lgkmcnt(0)
	s_barrier
; #define PG8_STAGE(bufoff, gbase, voff) do { _Pragma("unroll") for (int _i = 0; _i < 2; ++_i) \
;         __builtin_amdgcn_global_load_lds((const unsigned*)((const char*)(gbase) + (voff)[_i]), (PG8_LAS unsigned*)(lds + (bufoff) + ldsw + _i * 8192), 16, 0, 0); } while (0)
; #define PG8_LDA(dst, b, h) do { _Pragma("unroll") for (int m = 0; m < 4; ++m) _Pragma("unroll") for (int k = 0; k < 2; ++k) dst[m][k] = *(const PG8_LAS bf16x8*)(lds + PG8_SA(b, h) + aoff + m * 2048 + k * 1024); } while (0)
; #define PG8_LDB(dst, b, h) do { _Pragma("unroll") for (int n = 0; n < 2; ++n) _Pragma("unroll") for (int k = 0; k < 2; ++k) dst[n][k] = *(const PG8_LAS bf16x8*)(lds + PG8_SB(b, h) + boff + n * 2048 + k * 1024); } while (0)
; #define PG8_MMA(ai, bj, At, Bt) do { __builtin_amdgcn_s_setprio(1); _Pragma("unroll") for (int m = 0; m < 4; ++m) _Pragma("unroll") for (int n = 0; n < 2; ++n) _Pragma("unroll") for (int k = 0; k < 2; ++k) \
;         acc[ai][bj][m][n] = __builtin_amdgcn_mfma_f32_16x16x32_bf16(Bt[n][k], At[m][k], acc[ai][bj][m][n], 0, 0, 0); __builtin_amdgcn_s_setprio(0); } while (0)
; #define PG8_WAIT_V(n) asm volatile("s_waitcnt vmcnt(" #n ")" ::: "memory")
; #define PG8_WAIT_L(n) asm volatile("s_waitcnt lgkmcnt(" #n ")" ::: "memory")
; #define PG8_BAR __builtin_amdgcn_s_barrier()
; #define PG8_SCHED __builtin_amdgcn_sched_barrier(0)
; template <class Epi, class Sched, bool ALIGN_EPI = false, bool SP2 = false>
; __device__ __forceinline__ void gemm_phase(PG8_LAS unsigned char* lds, const Gemm g, const Sched& S, const Epi& E) {
;     ...
;             PG8_WAIT_V(8); PG8_WAIT_L(0); PG8_BAR; PG8_MMA(1, 0, At, B0); PG8_MMA(1, 1, At, B1); PG8_BAR; PG8_SCHED;
;             PG8_LDB(B0, 1, 0); PG8_LDB(B1, 1, 1); PG8_SCHED; PG8_LDA(At, 1, 0); PG8_STAGE(PG8_SA(0, 1), a2 + hstep, voffA);
;             PG8_WAIT_V(8); PG8_WAIT_L(0); PG8_BAR; PG8_MMA(0, 0, At, B0); PG8_MMA(0, 1, At, B1); PG8_BAR; PG8_SCHED;
	s_setprio 1
	s_waitcnt lgkmcnt(0)
	v_mfma_f32_16x16x32_bf16 v[66:69], v[142:145], v[182:185], v[66:69]
	v_mfma_f32_16x16x32_bf16 v[66:69], v[146:149], v[186:189], v[66:69]
	v_mfma_f32_16x16x32_bf16 v[62:65], v[162:165], v[186:189], v[62:65]
	v_mfma_f32_16x16x32_bf16 v[62:65], v[150:153], v[182:185], v[62:65]
	v_mfma_f32_16x16x32_bf16 v[46:49], v[150:153], v[190:193], v[46:49]
	v_mfma_f32_16x16x32_bf16 v[46:49], v[162:165], v[194:197], v[46:49]
	v_mfma_f32_16x16x32_bf16 v[50:53], v[146:149], v[194:197], v[50:53]
	v_mfma_f32_16x16x32_bf16 v[50:53], v[142:145], v[190:193], v[50:53]
	v_mfma_f32_16x16x32_bf16 v[34:37], v[142:145], v[198:201], v[34:37]
	v_mfma_f32_16x16x32_bf16 v[34:37], v[146:149], v[206:209], v[34:37]
	v_mfma_f32_16x16x32_bf16 v[30:33], v[162:165], v[206:209], v[30:33]
	v_mfma_f32_16x16x32_bf16 v[30:33], v[150:153], v[198:201], v[30:33]
	v_mfma_f32_16x16x32_bf16 v[10:13], v[150:153], v[210:213], v[10:13]
	v_mfma_f32_16x16x32_bf16 v[10:13], v[162:165], v[214:217], v[10:13]
	v_mfma_f32_16x16x32_bf16 v[18:21], v[146:149], v[214:217], v[18:21]
	v_mfma_f32_16x16x32_bf16 v[18:21], v[142:145], v[210:213], v[18:21]
	s_setprio 0
	s_setprio 1
	v_mfma_f32_16x16x32_bf16 v[58:61], v[166:169], v[182:185], v[58:61]
	v_mfma_f32_16x16x32_bf16 v[58:61], v[170:173], v[186:189], v[58:61]
	v_mfma_f32_16x16x32_bf16 v[54:57], v[178:181], v[186:189], v[54:57]
	v_mfma_f32_16x16x32_bf16 v[54:57], v[174:177], v[182:185], v[54:57]
	v_mfma_f32_16x16x32_bf16 v[38:41], v[174:177], v[190:193], v[38:41]
	v_mfma_f32_16x16x32_bf16 v[38:41], v[178:181], v[194:197], v[38:41]
	v_mfma_f32_16x16x32_bf16 v[42:45], v[170:173], v[194:197], v[42:45]
	v_mfma_f32_16x16x32_bf16 v[42:45], v[166:169], v[190:193], v[42:45]
	v_mfma_f32_16x16x32_bf16 v[26:29], v[166:169], v[198:201], v[26:29]
	v_mfma_f32_16x16x32_bf16 v[26:29], v[170:173], v[206:209], v[26:29]
	v_mfma_f32_16x16x32_bf16 v[22:25], v[178:181], v[206:209], v[22:25]
	v_mfma_f32_16x16x32_bf16 v[22:25], v[174:177], v[198:201], v[22:25]
	v_mfma_f32_16x16x32_bf16 v[2:5], v[174:177], v[210:213], v[2:5]
	v_mfma_f32_16x16x32_bf16 v[2:5], v[178:181], v[214:217], v[2:5]
	v_mfma_f32_16x16x32_bf16 v[6:9], v[170:173], v[214:217], v[6:9]
	v_mfma_f32_16x16x32_bf16 v[6:9], v[166:169], v[210:213], v[6:9]
	s_setprio 0
	s_barrier
	s_add_i32 s33, 0, 0x18000
	v_add_u32_e32 v161, s33, v155
	s_add_i32 s57, 0, 0x1c000
	ds_read_b128 v[142:145], v161
	ds_read_b128 v[146:149], v161 offset:1024
	ds_read_b128 v[150:153], v161 offset:2048
	ds_read_b128 v[162:165], v161 offset:3072
	v_add_u32_e32 v161, s57, v155
	ds_read_b128 v[166:169], v161
	ds_read_b128 v[170:173], v161 offset:1024
	ds_read_b128 v[174:177], v161 offset:2048
	ds_read_b128 v[178:181], v161 offset:3072
	s_add_u32 s30, s30, 0x80000
	s_addc_u32 s31, s31, 0
	s_mov_b32 m0, s44
	v_lshl_add_u64 v[224:225], s[30:31], 0, v[136:137]
	ds_read_b128 v[182:185], v160 offset:32768
	ds_read_b128 v[186:189], v160 offset:33792
	ds_read_b128 v[190:193], v160 offset:34816
	ds_read_b128 v[194:197], v160 offset:35840
	ds_read_b128 v[198:201], v160 offset:36864
	ds_read_b128 v[206:209], v160 offset:37888
	ds_read_b128 v[210:213], v160 offset:38912
	ds_read_b128 v[214:217], v160 offset:39936
	global_load_lds_dwordx4 v136, s[30:31]
	v_lshl_add_u64 v[224:225], s[30:31], 0, v[134:135]
	s_mov_b32 m0, s45
	s_nop 0
	global_load_lds_dwordx4 v134, s[30:31]
	s_waitcnt vmcnt(8)
	s_waitcnt lgkmcnt(0)
	s_barrier
	s_setprio 1
	s_waitcnt lgkmcnt(0)
	v_mfma_f32_16x16x32_bf16 v[130:133], v[142:145], v[182:185], v[130:133]
	v_mfma_f32_16x16x32_bf16 v[130:133], v[146:149], v[186:189], v[130:133]
	v_mfma_f32_16x16x32_bf16 v[126:129], v[162:165], v[186:189], v[126:129]
	v_mfma_f32_16x16x32_bf16 v[126:129], v[150:153], v[182:185], v[126:129]
	v_mfma_f32_16x16x32_bf16 v[110:113], v[150:153], v[190:193], v[110:113]
	v_mfma_f32_16x16x32_bf16 v[110:113], v[162:165], v[194:197], v[110:113]
	v_mfma_f32_16x16x32_bf16 v[114:117], v[146:149], v[194:197], v[114:117]
	v_mfma_f32_16x16x32_bf16 v[114:117], v[142:145], v[190:193], v[114:117]
	v_mfma_f32_16x16x32_bf16 v[98:101], v[142:145], v[198:201], v[98:101]
	v_mfma_f32_16x16x32_bf16 v[98:101], v[146:149], v[206:209], v[98:101]
	v_mfma_f32_16x16x32_bf16 v[94:97], v[162:165], v[206:209], v[94:97]
	v_mfma_f32_16x16x32_bf16 v[94:97], v[150:153], v[198:201], v[94:97]
	v_mfma_f32_16x16x32_bf16 v[78:81], v[150:153], v[210:213], v[78:81]
	v_mfma_f32_16x16x32_bf16 v[78:81], v[162:165], v[214:217], v[78:81]
	v_mfma_f32_16x16x32_bf16 v[82:85], v[146:149], v[214:217], v[82:85]
	v_mfma_f32_16x16x32_bf16 v[82:85], v[142:145], v[210:213], v[82:85]
	s_setprio 0
	s_setprio 1
	v_mfma_f32_16x16x32_bf16 v[122:125], v[166:169], v[182:185], v[122:125]
	v_mfma_f32_16x16x32_bf16 v[122:125], v[170:173], v[186:189], v[122:125]
	v_mfma_f32_16x16x32_bf16 v[118:121], v[178:181], v[186:189], v[118:121]
	v_mfma_f32_16x16x32_bf16 v[118:121], v[174:177], v[182:185], v[118:121]
	v_mfma_f32_16x16x32_bf16 v[102:105], v[174:177], v[190:193], v[102:105]
	v_mfma_f32_16x16x32_bf16 v[102:105], v[178:181], v[194:197], v[102:105]
	v_mfma_f32_16x16x32_bf16 v[106:109], v[170:173], v[194:197], v[106:109]
	v_mfma_f32_16x16x32_bf16 v[106:109], v[166:169], v[190:193], v[106:109]
	v_mfma_f32_16x16x32_bf16 v[90:93], v[166:169], v[198:201], v[90:93]
	v_mfma_f32_16x16x32_bf16 v[90:93], v[170:173], v[206:209], v[90:93]
	v_mfma_f32_16x16x32_bf16 v[86:89], v[178:181], v[206:209], v[86:89]
	v_mfma_f32_16x16x32_bf16 v[86:89], v[174:177], v[198:201], v[86:89]
	v_mfma_f32_16x16x32_bf16 v[70:73], v[174:177], v[210:213], v[70:73]
	v_mfma_f32_16x16x32_bf16 v[70:73], v[178:181], v[214:217], v[70:73]
	v_mfma_f32_16x16x32_bf16 v[74:77], v[170:173], v[214:217], v[74:77]
	v_mfma_f32_16x16x32_bf16 v[74:77], v[166:169], v[210:213], v[74:77]
	s_setprio 0
	s_barrier
; #define PG8_STAGE(bufoff, gbase, voff) do { _Pragma("unroll") for (int _i = 0; _i < 2; ++_i) \
;         __builtin_amdgcn_global_load_lds((const unsigned*)((const char*)(gbase) + (voff)[_i]), (PG8_LAS unsigned*)(lds + (bufoff) + ldsw + _i * 8192), 16, 0, 0); } while (0)
; #define PG8_LDA(dst, b, h) do { _Pragma("unroll") for (int m = 0; m < 4; ++m) _Pragma("unroll") for (int k = 0; k < 2; ++k) dst[m][k] = *(const PG8_LAS bf16x8*)(lds + PG8_SA(b, h) + aoff + m * 2048 + k * 1024); } while (0)
; #define PG8_MMA(ai, bj, At, Bt) do { __builtin_amdgcn_s_setprio(1); _Pragma("unroll") for (int m = 0; m < 4; ++m) _Pragma("unroll") for (int n = 0; n < 2; ++n) _Pragma("unroll") for (int k = 0; k < 2; ++k) \
;         acc[ai][bj][m][n] = __builtin_amdgcn_mfma_f32_16x16x32_bf16(Bt[n][k], At[m][k], acc[ai][bj][m][n], 0, 0, 0); __builtin_amdgcn_s_setprio(0); } while (0)
; #define PG8_WAIT_V(n) asm volatile("s_waitcnt vmcnt(" #n ")" ::: "memory")
; #define PG8_WAIT_L(n) asm volatile("s_waitcnt lgkmcnt(" #n ")" ::: "memory")
; #define PG8_BAR __builtin_amdgcn_s_barrier()
; #define PG8_SCHED __builtin_amdgcn_sched_barrier(0)
; template <class Epi, class Sched, bool ALIGN_EPI = false, bool SP2 = false>
; __device__ __forceinline__ void gemm_phase(PG8_LAS unsigned char* lds, const Gemm g, const Sched& S, const Epi& E) {
;     ...
;             PG8_LDA(At, 1, 1); PG8_STAGE(PG8_SB(1, 0), b3, voffB); PG8_STAGE(PG8_SB(1, 1), b3 + hstep, voffB); PG8_STAGE(PG8_SA(1, 0), a3, voffA);
;             PG8_WAIT_V(8); PG8_WAIT_L(0); PG8_BAR; PG8_MMA(1, 0, At, B0); PG8_MMA(1, 1, At, B1); PG8_BAR; PG8_SCHED;
;     ...
;         if constexpr (ALIGN_EPI) { if (wr == 0) PG8_BAR; }
	s_add_i32 s30, s33, s40
	v_lshl_add_u64 v[202:203], v[202:203], 0, s[92:93]
	s_mov_b32 m0, s30
	ds_read_b128 v[182:185], v160 offset:49152
	ds_read_b128 v[186:189], v160 offset:50176
	ds_read_b128 v[190:193], v160 offset:51200
	ds_read_b128 v[194:197], v160 offset:52224
	ds_read_b128 v[198:201], v160 offset:53248
	ds_read_b128 v[206:209], v160 offset:54272
	ds_read_b128 v[210:213], v160 offset:55296
	ds_read_b128 v[214:217], v160 offset:56320
	global_load_lds_dwordx4 v[202:203], off
	s_add_i32 m0, s30, 0x2000
	s_add_u32 s28, s28, 0x80080
	v_lshl_add_u64 v[202:203], v[218:219], 0, s[92:93]
	s_addc_u32 s29, s29, 0
	s_add_i32 s30, s57, s40
	global_load_lds_dwordx4 v[202:203], off
	v_lshl_add_u64 v[202:203], s[28:29], 0, v[0:1]
	s_mov_b32 m0, s30
	s_nop 0
	global_load_lds_dwordx4 v0, s[28:29]
	v_lshl_add_u64 v[202:203], s[28:29], 0, v[14:15]
	s_add_i32 m0, s30, 0x2000
	s_nop 0
	global_load_lds_dwordx4 v14, s[28:29]
	v_lshl_add_u64 v[202:203], v[220:221], 0, s[92:93]
	s_mov_b32 m0, s47
	s_nop 0
	global_load_lds_dwordx4 v[202:203], off
	v_lshl_add_u64 v[202:203], v[222:223], 0, s[92:93]
	s_mov_b32 m0, s48
	s_nop 0
	global_load_lds_dwordx4 v[202:203], off
	s_waitcnt vmcnt(8)
	s_waitcnt lgkmcnt(0)
	s_barrier
	s_setprio 1
	s_waitcnt lgkmcnt(0)
	v_mfma_f32_16x16x32_bf16 v[66:69], v[142:145], v[182:185], v[66:69]
	v_mfma_f32_16x16x32_bf16 v[66:69], v[146:149], v[186:189], v[66:69]
	v_mfma_f32_16x16x32_bf16 v[62:65], v[162:165], v[186:189], v[62:65]
	v_mfma_f32_16x16x32_bf16 v[62:65], v[150:153], v[182:185], v[62:65]
	v_mfma_f32_16x16x32_bf16 v[46:49], v[150:153], v[190:193], v[46:49]
	v_mfma_f32_16x16x32_bf16 v[46:49], v[162:165], v[194:197], v[46:49]
	v_mfma_f32_16x16x32_bf16 v[50:53], v[146:149], v[194:197], v[50:53]
	v_mfma_f32_16x16x32_bf16 v[50:53], v[142:145], v[190:193], v[50:53]
	v_mfma_f32_16x16x32_bf16 v[34:37], v[142:145], v[198:201], v[34:37]
	v_mfma_f32_16x16x32_bf16 v[34:37], v[146:149], v[206:209], v[34:37]
	v_mfma_f32_16x16x32_bf16 v[30:33], v[162:165], v[206:209], v[30:33]
	v_mfma_f32_16x16x32_bf16 v[30:33], v[150:153], v[198:201], v[30:33]
	v_mfma_f32_16x16x32_bf16 v[10:13], v[150:153], v[210:213], v[10:13]
	v_mfma_f32_16x16x32_bf16 v[10:13], v[162:165], v[214:217], v[10:13]
	v_mfma_f32_16x16x32_bf16 v[18:21], v[146:149], v[214:217], v[18:21]
	v_mfma_f32_16x16x32_bf16 v[18:21], v[142:145], v[210:213], v[18:21]
	s_setprio 0
	s_setprio 1
	v_mfma_f32_16x16x32_bf16 v[58:61], v[166:169], v[182:185], v[58:61]
	v_mfma_f32_16x16x32_bf16 v[58:61], v[170:173], v[186:189], v[58:61]
	v_mfma_f32_16x16x32_bf16 v[54:57], v[178:181], v[186:189], v[54:57]
	v_mfma_f32_16x16x32_bf16 v[54:57], v[174:177], v[182:185], v[54:57]
	v_mfma_f32_16x16x32_bf16 v[38:41], v[174:177], v[190:193], v[38:41]
	v_mfma_f32_16x16x32_bf16 v[38:41], v[178:181], v[194:197], v[38:41]
	v_mfma_f32_16x16x32_bf16 v[42:45], v[170:173], v[194:197], v[42:45]
	v_mfma_f32_16x16x32_bf16 v[42:45], v[166:169], v[190:193], v[42:45]
	v_mfma_f32_16x16x32_bf16 v[26:29], v[166:169], v[198:201], v[26:29]
	v_mfma_f32_16x16x32_bf16 v[26:29], v[170:173], v[206:209], v[26:29]
	v_mfma_f32_16x16x32_bf16 v[22:25], v[178:181], v[206:209], v[22:25]
	v_mfma_f32_16x16x32_bf16 v[22:25], v[174:177], v[198:201], v[22:25]
	v_mfma_f32_16x16x32_bf16 v[2:5], v[174:177], v[210:213], v[2:5]
	v_mfma_f32_16x16x32_bf16 v[2:5], v[178:181], v[214:217], v[2:5]
	v_mfma_f32_16x16x32_bf16 v[6:9], v[170:173], v[214:217], v[6:9]
	v_mfma_f32_16x16x32_bf16 v[6:9], v[166:169], v[210:213], v[6:9]
	s_setprio 0
	s_barrier
	s_add_i32 s56, s56, 2
	s_add_u32 s54, s54, 0x100
	s_addc_u32 s55, s55, 0
	s_add_u32 s26, s26, 0x100
	s_addc_u32 s27, s27, 0
	s_cmp_gt_u32 s56, 29
	s_cbranch_scc0 .LBB0_1223
	s_and_b64 vcc, exec, s[14:15]
	s_cbranch_vccz .LBB0_1226
	s_barrier

; #define PG8_STAGE(bufoff, gbase, voff) do { _Pragma("unroll") for (int _i = 0; _i < 2; ++_i) \
;         __builtin_amdgcn_global_load_lds((const unsigned*)((const char*)(gbase) + (voff)[_i]), (PG8_LAS unsigned*)(lds + (bufoff) + ldsw + _i * 8192), 16, 0, 0); } while (0)
; #define PG8_LDA(dst, b, h) do { _Pragma("unroll") for (int m = 0; m < 4; ++m) _Pragma("unroll") for (int k = 0; k < 2; ++k) dst[m][k] = *(const PG8_LAS bf16x8*)(lds + PG8_SA(b, h) + aoff + m * 2048 + k * 1024); } while (0)
; #define PG8_LDB(dst, b, h) do { _Pragma("unroll") for (int n = 0; n < 2; ++n) _Pragma("unroll") for (int k = 0; k < 2; ++k) dst[n][k] = *(const PG8_LAS bf16x8*)(lds + PG8_SB(b, h) + boff + n * 2048 + k * 1024); } while (0)
; #define PG8_WAIT_V(n) asm volatile("s_waitcnt vmcnt(" #n ")" ::: "memory")
; #define PG8_WAIT_L(n) asm volatile("s_waitcnt lgkmcnt(" #n ")" ::: "memory")
; #define PG8_BAR __builtin_amdgcn_s_barrier()
; #define PG8_SCHED __builtin_amdgcn_sched_barrier(0)
; template <class Epi, class Sched, bool ALIGN_EPI = false, bool SP2 = false>
; __device__ __forceinline__ void gemm_phase(PG8_LAS unsigned char* lds, const Gemm g, const Sched& S, const Epi& E) {
;     ...
;         const bool has_next = S.next(ui + 1, nxt);
;         const char* nA = has_next ? (const char*)g.A + (size_t)nxt.pm * tstep : cA; const char* nB = has_next ? (const char*)g.Bt + (size_t)nxt.pn * tstep : cB;
;         for (int t = 0; t < nt; t += 2) {
;             const bool last = (t == nt - 2);
;             const char* a1 = cA + (size_t)(t + 1) * kstep;
;             const char* a2 = last ? nA : cA + (size_t)(t + 2) * kstep; const char* b2 = last ? nB : cB + (size_t)(t + 2) * kstep;
;             const char* a3 = a2 + kstep; const char* b3 = b2 + kstep;
;             if (last && has_next) S.a_ready(nxt);
;             if constexpr (Epi::MID) { if (t == nt / 2) E.mid(acc, cur, wr, wc, fr, fq); }
;             if constexpr (SP2) {
;             PG8_LDB(B0, 0, 0); PG8_LDB(B1, 0, 1); PG8_SCHED; PG8_LDA(At, 0, 0); PG8_STAGE(PG8_SA(1, 1), a1 + hstep, voffA);
;             PG8_WAIT_V(8); PG8_WAIT_L(0); PG8_BAR; PG8_MMA(0, 0, At, B0); PG8_MMA(0, 1, At, B1); PG8_BAR; PG8_SCHED;
;             PG8_LDA(At, 0, 1); PG8_STAGE(PG8_SB(0, 0), b2, voffB); PG8_STAGE(PG8_SB(0, 1), b2 + hstep, voffB); PG8_STAGE(PG8_SA(0, 0), a2, voffA);
.LBB0_1329:
	s_add_u32 s4, s24, 0x100
	s_addc_u32 s5, s25, 0
	s_add_i32 s33, 0, 0x10000
	s_cmpk_eq_i32 s53, 0x54
	s_cselect_b32 s29, s21, s5
	s_cselect_b32 s28, s20, s4
	s_cselect_b32 s27, s23, s52
	s_cselect_b32 s26, s22, s51
	s_add_i32 s54, 0, 0x14000
	v_add_u32_e32 v98, s33, v199
	v_add_u32_e32 v146, s54, v199
	ds_read_b128 v[70:73], v98
	ds_read_b128 v[74:77], v98 offset:1024
	ds_read_b128 v[86:89], v98 offset:2048
	ds_read_b128 v[98:101], v98 offset:3072
	ds_read_b128 v[110:113], v146
	ds_read_b128 v[122:125], v146 offset:1024
	ds_read_b128 v[134:137], v146 offset:2048
	ds_read_b128 v[146:149], v146 offset:3072
	v_lshl_add_u64 v[202:203], s[24:25], 0, v[208:209]
	s_add_i32 m0, s39, 0xc000
	ds_read_b128 v[158:161], v201
	ds_read_b128 v[162:165], v201 offset:1024
	ds_read_b128 v[174:177], v201 offset:2048
	ds_read_b128 v[178:181], v201 offset:3072
	ds_read_b128 v[182:185], v201 offset:4096
	ds_read_b128 v[186:189], v201 offset:5120
	ds_read_b128 v[190:193], v201 offset:6144
	ds_read_b128 v[210:213], v201 offset:7168
	global_load_lds_dwordx4 v208, s[24:25]
	v_lshl_add_u64 v[202:203], s[24:25], 0, v[206:207]
	s_add_i32 m0, s39, 0xe000
	s_nop 0
	global_load_lds_dwordx4 v206, s[24:25]
	s_waitcnt vmcnt(8)
	s_waitcnt lgkmcnt(0)
	s_barrier
	s_setprio 1
	s_waitcnt lgkmcnt(0)
	v_mfma_f32_16x16x32_bf16 v[170:173], v[70:73], v[158:161], v[170:173]
	v_mfma_f32_16x16x32_bf16 v[170:173], v[74:77], v[162:165], v[170:173]
	v_mfma_f32_16x16x32_bf16 v[166:169], v[98:101], v[162:165], v[166:169]
	v_mfma_f32_16x16x32_bf16 v[166:169], v[86:89], v[158:161], v[166:169]
	v_mfma_f32_16x16x32_bf16 v[138:141], v[86:89], v[174:177], v[138:141]
	v_mfma_f32_16x16x32_bf16 v[138:141], v[98:101], v[178:181], v[138:141]
	v_mfma_f32_16x16x32_bf16 v[142:145], v[74:77], v[178:181], v[142:145]
	v_mfma_f32_16x16x32_bf16 v[142:145], v[70:73], v[174:177], v[142:145]
	v_mfma_f32_16x16x32_bf16 v[118:121], v[70:73], v[182:185], v[118:121]
	v_mfma_f32_16x16x32_bf16 v[118:121], v[74:77], v[186:189], v[118:121]
	v_mfma_f32_16x16x32_bf16 v[114:117], v[98:101], v[186:189], v[114:117]
	v_mfma_f32_16x16x32_bf16 v[114:117], v[86:89], v[182:185], v[114:117]
	v_mfma_f32_16x16x32_bf16 v[90:93], v[86:89], v[190:193], v[90:93]
	v_mfma_f32_16x16x32_bf16 v[90:93], v[98:101], v[210:213], v[90:93]
	v_mfma_f32_16x16x32_bf16 v[94:97], v[74:77], v[210:213], v[94:97]
	v_mfma_f32_16x16x32_bf16 v[94:97], v[70:73], v[190:193], v[94:97]
	s_setprio 0
	s_setprio 1
	v_mfma_f32_16x16x32_bf16 v[154:157], v[110:113], v[158:161], v[154:157]
	v_mfma_f32_16x16x32_bf16 v[154:157], v[122:125], v[162:165], v[154:157]
	v_mfma_f32_16x16x32_bf16 v[150:153], v[146:149], v[162:165], v[150:153]
	v_mfma_f32_16x16x32_bf16 v[150:153], v[134:137], v[158:161], v[150:153]
	v_mfma_f32_16x16x32_bf16 v[126:129], v[134:137], v[174:177], v[126:129]
	v_mfma_f32_16x16x32_bf16 v[126:129], v[146:149], v[178:181], v[126:129]
	v_mfma_f32_16x16x32_bf16 v[130:133], v[122:125], v[178:181], v[130:133]
	v_mfma_f32_16x16x32_bf16 v[130:133], v[110:113], v[174:177], v[130:133]
	v_mfma_f32_16x16x32_bf16 v[106:109], v[110:113], v[182:185], v[106:109]
	v_mfma_f32_16x16x32_bf16 v[106:109], v[122:125], v[186:189], v[106:109]
	v_mfma_f32_16x16x32_bf16 v[102:105], v[146:149], v[186:189], v[102:105]
	v_mfma_f32_16x16x32_bf16 v[102:105], v[134:137], v[182:185], v[102:105]
	v_mfma_f32_16x16x32_bf16 v[78:81], v[134:137], v[190:193], v[78:81]
	v_mfma_f32_16x16x32_bf16 v[78:81], v[146:149], v[210:213], v[78:81]
	v_mfma_f32_16x16x32_bf16 v[82:85], v[122:125], v[210:213], v[82:85]
	v_mfma_f32_16x16x32_bf16 v[82:85], v[110:113], v[190:193], v[82:85]
	s_setprio 0
	s_barrier
	s_add_i32 s24, s33, s38
	v_lshl_add_u64 v[202:203], s[26:27], 0, v[0:1]
	s_mov_b32 m0, s24
	ds_read_b128 v[158:161], v201 offset:16384
	ds_read_b128 v[162:165], v201 offset:17408
	ds_read_b128 v[174:177], v201 offset:18432
	ds_read_b128 v[178:181], v201 offset:19456
	ds_read_b128 v[182:185], v201 offset:20480
	ds_read_b128 v[186:189], v201 offset:21504
	ds_read_b128 v[190:193], v201 offset:22528
	ds_read_b128 v[210:213], v201 offset:23552
	global_load_lds_dwordx4 v0, s[26:27]
	s_add_i32 m0, s24, 0x2000
	s_add_u32 s24, s26, 0x160000
	v_lshl_add_u64 v[214:215], s[26:27], 0, v[196:197]
	s_addc_u32 s25, s27, 0
	s_add_i32 s33, s54, s38
	global_load_lds_dwordx4 v196, s[26:27]
	v_lshl_add_u64 v[216:217], s[24:25], 0, v[0:1]
	s_mov_b32 m0, s33
	v_lshl_add_u64 v[218:219], s[28:29], 0, v[194:195]
	global_load_lds_dwordx4 v0, s[24:25]
	v_lshl_add_u64 v[216:217], s[24:25], 0, v[196:197]
	s_add_i32 m0, s33, 0x2000
	s_nop 0
	global_load_lds_dwordx4 v196, s[24:25]
	v_lshl_add_u64 v[216:217], s[28:29], 0, v[14:15]
	s_mov_b32 m0, s39
	s_nop 0
	global_load_lds_dwordx4 v14, s[28:29]
	s_mov_b32 m0, s40
	s_nop 0
	global_load_lds_dwordx4 v194, s[28:29]
	s_waitcnt vmcnt(8)
	s_waitcnt lgkmcnt(0)
	s_barrier
; #define PG8_STAGE(bufoff, gbase, voff) do { _Pragma("unroll") for (int _i = 0; _i < 2; ++_i) \
;         __builtin_amdgcn_global_load_lds((const unsigned*)((const char*)(gbase) + (voff)[_i]), (PG8_LAS unsigned*)(lds + (bufoff) + ldsw + _i * 8192), 16, 0, 0); } while (0)
; #define PG8_LDA(dst, b, h) do { _Pragma("unroll") for (int m = 0; m < 4; ++m) _Pragma("unroll") for (int k = 0; k < 2; ++k) dst[m][k] = *(const PG8_LAS bf16x8*)(lds + PG8_SA(b, h) + aoff + m * 2048 + k * 1024); } while (0)
; #define PG8_LDB(dst, b, h) do { _Pragma("unroll") for (int n = 0; n < 2; ++n) _Pragma("unroll") for (int k = 0; k < 2; ++k) dst[n][k] = *(const PG8_LAS bf16x8*)(lds + PG8_SB(b, h) + boff + n * 2048 + k * 1024); } while (0)
; #define PG8_MMA(ai, bj, At, Bt) do { __builtin_amdgcn_s_setprio(1); _Pragma("unroll") for (int m = 0; m < 4; ++m) _Pragma("unroll") for (int n = 0; n < 2; ++n) _Pragma("unroll") for (int k = 0; k < 2; ++k) \
;         acc[ai][bj][m][n] = __builtin_amdgcn_mfma_f32_16x16x32_bf16(Bt[n][k], At[m][k], acc[ai][bj][m][n], 0, 0, 0); __builtin_amdgcn_s_setprio(0); } while (0)
; #define PG8_WAIT_V(n) asm volatile("s_waitcnt vmcnt(" #n ")" ::: "memory")
; #define PG8_WAIT_L(n) asm volatile("s_waitcnt lgkmcnt(" #n ")" ::: "memory")
; #define PG8_BAR __builtin_amdgcn_s_barrier()
; #define PG8_SCHED __builtin_amdgcn_sched_barrier(0)
; template <class Epi, class Sched, bool ALIGN_EPI = false, bool SP2 = false>
; __device__ __forceinline__ void gemm_phase(PG8_LAS unsigned char* lds, const Gemm g, const Sched& S, const Epi& E) {
;     ...
;             PG8_WAIT_V(8); PG8_WAIT_L(0); PG8_BAR; PG8_MMA(1, 0, At, B0); PG8_MMA(1, 1, At, B1); PG8_BAR; PG8_SCHED;
;             PG8_LDB(B0, 1, 0); PG8_LDB(B1, 1, 1); PG8_SCHED; PG8_LDA(At, 1, 0); PG8_STAGE(PG8_SA(0, 1), a2 + hstep, voffA);
;             PG8_WAIT_V(8); PG8_WAIT_L(0); PG8_BAR; PG8_MMA(0, 0, At, B0); PG8_MMA(0, 1, At, B1); PG8_BAR; PG8_SCHED;
	s_setprio 1
	s_waitcnt lgkmcnt(0)
	v_mfma_f32_16x16x32_bf16 v[66:69], v[70:73], v[158:161], v[66:69]
	v_mfma_f32_16x16x32_bf16 v[66:69], v[74:77], v[162:165], v[66:69]
	v_mfma_f32_16x16x32_bf16 v[62:65], v[98:101], v[162:165], v[62:65]
	v_mfma_f32_16x16x32_bf16 v[62:65], v[86:89], v[158:161], v[62:65]
	v_mfma_f32_16x16x32_bf16 v[46:49], v[86:89], v[174:177], v[46:49]
	v_mfma_f32_16x16x32_bf16 v[46:49], v[98:101], v[178:181], v[46:49]
	v_mfma_f32_16x16x32_bf16 v[50:53], v[74:77], v[178:181], v[50:53]
	v_mfma_f32_16x16x32_bf16 v[50:53], v[70:73], v[174:177], v[50:53]
	v_mfma_f32_16x16x32_bf16 v[34:37], v[70:73], v[182:185], v[34:37]
	v_mfma_f32_16x16x32_bf16 v[34:37], v[74:77], v[186:189], v[34:37]
	v_mfma_f32_16x16x32_bf16 v[30:33], v[98:101], v[186:189], v[30:33]
	v_mfma_f32_16x16x32_bf16 v[30:33], v[86:89], v[182:185], v[30:33]
	v_mfma_f32_16x16x32_bf16 v[10:13], v[86:89], v[190:193], v[10:13]
	v_mfma_f32_16x16x32_bf16 v[10:13], v[98:101], v[210:213], v[10:13]
	v_mfma_f32_16x16x32_bf16 v[18:21], v[74:77], v[210:213], v[18:21]
	v_mfma_f32_16x16x32_bf16 v[18:21], v[70:73], v[190:193], v[18:21]
	s_setprio 0
	s_setprio 1
	v_mfma_f32_16x16x32_bf16 v[58:61], v[110:113], v[158:161], v[58:61]
	v_mfma_f32_16x16x32_bf16 v[58:61], v[122:125], v[162:165], v[58:61]
	v_mfma_f32_16x16x32_bf16 v[54:57], v[146:149], v[162:165], v[54:57]
	v_mfma_f32_16x16x32_bf16 v[54:57], v[134:137], v[158:161], v[54:57]
	v_mfma_f32_16x16x32_bf16 v[38:41], v[134:137], v[174:177], v[38:41]
	v_mfma_f32_16x16x32_bf16 v[38:41], v[146:149], v[178:181], v[38:41]
	v_mfma_f32_16x16x32_bf16 v[42:45], v[122:125], v[178:181], v[42:45]
	v_mfma_f32_16x16x32_bf16 v[42:45], v[110:113], v[174:177], v[42:45]
	v_mfma_f32_16x16x32_bf16 v[26:29], v[110:113], v[182:185], v[26:29]
	v_mfma_f32_16x16x32_bf16 v[26:29], v[122:125], v[186:189], v[26:29]
	v_mfma_f32_16x16x32_bf16 v[22:25], v[146:149], v[186:189], v[22:25]
	v_mfma_f32_16x16x32_bf16 v[22:25], v[134:137], v[182:185], v[22:25]
	v_mfma_f32_16x16x32_bf16 v[2:5], v[134:137], v[190:193], v[2:5]
	v_mfma_f32_16x16x32_bf16 v[2:5], v[146:149], v[210:213], v[2:5]
	v_mfma_f32_16x16x32_bf16 v[6:9], v[122:125], v[210:213], v[6:9]
	v_mfma_f32_16x16x32_bf16 v[6:9], v[110:113], v[190:193], v[6:9]
	s_setprio 0
	s_barrier
	s_add_i32 s33, 0, 0x18000
	s_add_i32 s54, 0, 0x1c000
	v_add_u32_e32 v98, s33, v199
	v_add_u32_e32 v146, s54, v199
	ds_read_b128 v[70:73], v98
	ds_read_b128 v[74:77], v98 offset:1024
	ds_read_b128 v[86:89], v98 offset:2048
	ds_read_b128 v[98:101], v98 offset:3072
	ds_read_b128 v[110:113], v146
	ds_read_b128 v[122:125], v146 offset:1024
	ds_read_b128 v[134:137], v146 offset:2048
	ds_read_b128 v[146:149], v146 offset:3072
	s_add_u32 s24, s28, 0x160000
	s_addc_u32 s25, s29, 0
	s_mov_b32 m0, s41
	v_lshl_add_u64 v[220:221], s[24:25], 0, v[14:15]
	ds_read_b128 v[158:161], v201 offset:32768
	ds_read_b128 v[162:165], v201 offset:33792
	ds_read_b128 v[174:177], v201 offset:34816
	ds_read_b128 v[178:181], v201 offset:35840
	ds_read_b128 v[182:185], v201 offset:36864
	ds_read_b128 v[186:189], v201 offset:37888
	ds_read_b128 v[190:193], v201 offset:38912
	ds_read_b128 v[210:213], v201 offset:39936
	global_load_lds_dwordx4 v14, s[24:25]
	v_lshl_add_u64 v[220:221], s[24:25], 0, v[194:195]
	s_mov_b32 m0, s42
	s_nop 0
	global_load_lds_dwordx4 v194, s[24:25]
	s_waitcnt vmcnt(8)
	s_waitcnt lgkmcnt(0)
	s_barrier
	s_setprio 1
	s_waitcnt lgkmcnt(0)
	v_mfma_f32_16x16x32_bf16 v[170:173], v[70:73], v[158:161], v[170:173]
	v_mfma_f32_16x16x32_bf16 v[170:173], v[74:77], v[162:165], v[170:173]
	v_mfma_f32_16x16x32_bf16 v[166:169], v[98:101], v[162:165], v[166:169]
	v_mfma_f32_16x16x32_bf16 v[166:169], v[86:89], v[158:161], v[166:169]
	v_mfma_f32_16x16x32_bf16 v[138:141], v[86:89], v[174:177], v[138:141]
	v_mfma_f32_16x16x32_bf16 v[138:141], v[98:101], v[178:181], v[138:141]
	v_mfma_f32_16x16x32_bf16 v[142:145], v[74:77], v[178:181], v[142:145]
	v_mfma_f32_16x16x32_bf16 v[142:145], v[70:73], v[174:177], v[142:145]
	v_mfma_f32_16x16x32_bf16 v[118:121], v[70:73], v[182:185], v[118:121]
	v_mfma_f32_16x16x32_bf16 v[118:121], v[74:77], v[186:189], v[118:121]
	v_mfma_f32_16x16x32_bf16 v[114:117], v[98:101], v[186:189], v[114:117]
	v_mfma_f32_16x16x32_bf16 v[114:117], v[86:89], v[182:185], v[114:117]
	v_mfma_f32_16x16x32_bf16 v[90:93], v[86:89], v[190:193], v[90:93]
	v_mfma_f32_16x16x32_bf16 v[90:93], v[98:101], v[210:213], v[90:93]
	v_mfma_f32_16x16x32_bf16 v[94:97], v[74:77], v[210:213], v[94:97]
	v_mfma_f32_16x16x32_bf16 v[94:97], v[70:73], v[190:193], v[94:97]
	s_setprio 0
	s_setprio 1
	v_mfma_f32_16x16x32_bf16 v[154:157], v[110:113], v[158:161], v[154:157]
	v_mfma_f32_16x16x32_bf16 v[154:157], v[122:125], v[162:165], v[154:157]
	v_mfma_f32_16x16x32_bf16 v[150:153], v[146:149], v[162:165], v[150:153]
	v_mfma_f32_16x16x32_bf16 v[150:153], v[134:137], v[158:161], v[150:153]
	v_mfma_f32_16x16x32_bf16 v[126:129], v[134:137], v[174:177], v[126:129]
	v_mfma_f32_16x16x32_bf16 v[126:129], v[146:149], v[178:181], v[126:129]
	v_mfma_f32_16x16x32_bf16 v[130:133], v[122:125], v[178:181], v[130:133]
	v_mfma_f32_16x16x32_bf16 v[130:133], v[110:113], v[174:177], v[130:133]
	v_mfma_f32_16x16x32_bf16 v[106:109], v[110:113], v[182:185], v[106:109]
	v_mfma_f32_16x16x32_bf16 v[106:109], v[122:125], v[186:189], v[106:109]
	v_mfma_f32_16x16x32_bf16 v[102:105], v[146:149], v[186:189], v[102:105]
	v_mfma_f32_16x16x32_bf16 v[102:105], v[134:137], v[182:185], v[102:105]
	v_mfma_f32_16x16x32_bf16 v[78:81], v[134:137], v[190:193], v[78:81]
	v_mfma_f32_16x16x32_bf16 v[78:81], v[146:149], v[210:213], v[78:81]
	v_mfma_f32_16x16x32_bf16 v[82:85], v[122:125], v[210:213], v[82:85]
	v_mfma_f32_16x16x32_bf16 v[82:85], v[110:113], v[190:193], v[82:85]
	s_setprio 0
	s_barrier
; #define PG8_STAGE(bufoff, gbase, voff) do { _Pragma("unroll") for (int _i = 0; _i < 2; ++_i) \
;         __builtin_amdgcn_global_load_lds((const unsigned*)((const char*)(gbase) + (voff)[_i]), (PG8_LAS unsigned*)(lds + (bufoff) + ldsw + _i * 8192), 16, 0, 0); } while (0)
; #define PG8_LDA(dst, b, h) do { _Pragma("unroll") for (int m = 0; m < 4; ++m) _Pragma("unroll") for (int k = 0; k < 2; ++k) dst[m][k] = *(const PG8_LAS bf16x8*)(lds + PG8_SA(b, h) + aoff + m * 2048 + k * 1024); } while (0)
; #define PG8_MMA(ai, bj, At, Bt) do { __builtin_amdgcn_s_setprio(1); _Pragma("unroll") for (int m = 0; m < 4; ++m) _Pragma("unroll") for (int n = 0; n < 2; ++n) _Pragma("unroll") for (int k = 0; k < 2; ++k) \
;         acc[ai][bj][m][n] = __builtin_amdgcn_mfma_f32_16x16x32_bf16(Bt[n][k], At[m][k], acc[ai][bj][m][n], 0, 0, 0); __builtin_amdgcn_s_setprio(0); } while (0)
; #define PG8_WAIT_V(n) asm volatile("s_waitcnt vmcnt(" #n ")" ::: "memory")
; #define PG8_WAIT_L(n) asm volatile("s_waitcnt lgkmcnt(" #n ")" ::: "memory")
; #define PG8_BAR __builtin_amdgcn_s_barrier()
; #define PG8_SCHED __builtin_amdgcn_sched_barrier(0)
; template <class Epi, class Sched, bool ALIGN_EPI = false, bool SP2 = false>
; __device__ __forceinline__ void gemm_phase(PG8_LAS unsigned char* lds, const Gemm g, const Sched& S, const Epi& E) {
;     ...
;             PG8_LDA(At, 1, 1); PG8_STAGE(PG8_SB(1, 0), b3, voffB); PG8_STAGE(PG8_SB(1, 1), b3 + hstep, voffB); PG8_STAGE(PG8_SA(1, 0), a3, voffA);
;             PG8_WAIT_V(8); PG8_WAIT_L(0); PG8_BAR; PG8_MMA(1, 0, At, B0); PG8_MMA(1, 1, At, B1); PG8_BAR; PG8_SCHED;
;     ...
;         if constexpr (ALIGN_EPI) { if (wr == 0) PG8_BAR; }
	s_add_i32 s24, s33, s38
	v_lshl_add_u64 v[202:203], v[202:203], 0, s[92:93]
	s_mov_b32 m0, s24
	ds_read_b128 v[158:161], v201 offset:49152
	ds_read_b128 v[162:165], v201 offset:50176
	ds_read_b128 v[174:177], v201 offset:51200
	ds_read_b128 v[178:181], v201 offset:52224
	ds_read_b128 v[182:185], v201 offset:53248
	ds_read_b128 v[186:189], v201 offset:54272
	ds_read_b128 v[190:193], v201 offset:55296
	ds_read_b128 v[210:213], v201 offset:56320
	global_load_lds_dwordx4 v[202:203], off
	s_add_i32 m0, s24, 0x2000
	s_add_u32 s24, s26, 0x160080
	v_lshl_add_u64 v[202:203], v[214:215], 0, s[92:93]
	s_addc_u32 s25, s27, 0
	s_add_i32 s26, s54, s38
	global_load_lds_dwordx4 v[202:203], off
	v_lshl_add_u64 v[202:203], s[24:25], 0, v[0:1]
	s_mov_b32 m0, s26
	s_nop 0
	global_load_lds_dwordx4 v0, s[24:25]
	v_lshl_add_u64 v[202:203], s[24:25], 0, v[196:197]
	s_add_i32 m0, s26, 0x2000
	s_nop 0
	global_load_lds_dwordx4 v196, s[24:25]
	v_lshl_add_u64 v[202:203], v[216:217], 0, s[92:93]
	s_mov_b32 m0, s44
	s_nop 0
	global_load_lds_dwordx4 v[202:203], off
	v_lshl_add_u64 v[202:203], v[218:219], 0, s[92:93]
	s_mov_b32 m0, s45
	s_nop 0
	global_load_lds_dwordx4 v[202:203], off
	s_waitcnt vmcnt(8)
	s_waitcnt lgkmcnt(0)
	s_barrier
	s_setprio 1
	s_waitcnt lgkmcnt(0)
	v_mfma_f32_16x16x32_bf16 v[66:69], v[70:73], v[158:161], v[66:69]
	v_mfma_f32_16x16x32_bf16 v[66:69], v[74:77], v[162:165], v[66:69]
	v_mfma_f32_16x16x32_bf16 v[62:65], v[98:101], v[162:165], v[62:65]
	v_mfma_f32_16x16x32_bf16 v[62:65], v[86:89], v[158:161], v[62:65]
	v_mfma_f32_16x16x32_bf16 v[46:49], v[86:89], v[174:177], v[46:49]
	v_mfma_f32_16x16x32_bf16 v[46:49], v[98:101], v[178:181], v[46:49]
	v_mfma_f32_16x16x32_bf16 v[50:53], v[74:77], v[178:181], v[50:53]
	v_mfma_f32_16x16x32_bf16 v[50:53], v[70:73], v[174:177], v[50:53]
	v_mfma_f32_16x16x32_bf16 v[34:37], v[70:73], v[182:185], v[34:37]
	v_mfma_f32_16x16x32_bf16 v[34:37], v[74:77], v[186:189], v[34:37]
	v_mfma_f32_16x16x32_bf16 v[30:33], v[98:101], v[186:189], v[30:33]
	v_mfma_f32_16x16x32_bf16 v[30:33], v[86:89], v[182:185], v[30:33]
	v_mfma_f32_16x16x32_bf16 v[10:13], v[86:89], v[190:193], v[10:13]
	v_mfma_f32_16x16x32_bf16 v[10:13], v[98:101], v[210:213], v[10:13]
	v_mfma_f32_16x16x32_bf16 v[18:21], v[74:77], v[210:213], v[18:21]
	v_mfma_f32_16x16x32_bf16 v[18:21], v[70:73], v[190:193], v[18:21]
	s_setprio 0
	s_setprio 1
	v_mfma_f32_16x16x32_bf16 v[58:61], v[110:113], v[158:161], v[58:61]
	v_mfma_f32_16x16x32_bf16 v[58:61], v[122:125], v[162:165], v[58:61]
	v_mfma_f32_16x16x32_bf16 v[54:57], v[146:149], v[162:165], v[54:57]
	v_mfma_f32_16x16x32_bf16 v[54:57], v[134:137], v[158:161], v[54:57]
	v_mfma_f32_16x16x32_bf16 v[38:41], v[134:137], v[174:177], v[38:41]
	v_mfma_f32_16x16x32_bf16 v[38:41], v[146:149], v[178:181], v[38:41]
	v_mfma_f32_16x16x32_bf16 v[42:45], v[122:125], v[178:181], v[42:45]
	v_mfma_f32_16x16x32_bf16 v[42:45], v[110:113], v[174:177], v[42:45]
	v_mfma_f32_16x16x32_bf16 v[26:29], v[110:113], v[182:185], v[26:29]
	v_mfma_f32_16x16x32_bf16 v[26:29], v[122:125], v[186:189], v[26:29]
	v_mfma_f32_16x16x32_bf16 v[22:25], v[146:149], v[186:189], v[22:25]
	v_mfma_f32_16x16x32_bf16 v[22:25], v[134:137], v[182:185], v[22:25]
	v_mfma_f32_16x16x32_bf16 v[2:5], v[134:137], v[190:193], v[2:5]
	v_mfma_f32_16x16x32_bf16 v[2:5], v[146:149], v[210:213], v[2:5]
	v_mfma_f32_16x16x32_bf16 v[6:9], v[122:125], v[210:213], v[6:9]
	v_mfma_f32_16x16x32_bf16 v[6:9], v[110:113], v[190:193], v[6:9]
	s_setprio 0
	s_barrier
	s_add_i32 s53, s53, 2
	s_add_u32 s51, s51, 0x100
	s_addc_u32 s52, s52, 0
	s_cmpk_gt_u32 s53, 0x55
	s_mov_b64 s[24:25], s[4:5]
	s_cbranch_scc0 .LBB0_1329
	s_and_b64 vcc, exec, s[16:17]
	s_cbranch_vccz .LBB0_1332
	s_barrier
